# in-proj k-loop: fragment registers alternated between two sets (131 live ranges renamed) so next-step ds_reads issue before current MFMAs (225 reads hoisted)
# speedup vs baseline: 1.0050x; 1.0050x over previous
; #define MFMA(a, b, c) __builtin_amdgcn_mfma_f32_32x32x16_bf16((a), (b), (c), 0, 0, 0)
;     ...
;   const int tid = opaque_tid(), lane = tid & 63, h = lane >> 5, r = lane & 31;
;   const int nk = K >> 6;
;   const int cch = (tid & 7) ^ ((tid >> 4) & 7);
;   const u16* ga = A + (size_t)(tid >> 3) * lda + cch * 8;
;   const u16* gb = Bt + (size_t)(tid >> 3) * ldb + cch * 8;
;   char* lds_t = smem + tid * 16;
;   auto issue_piece = [&](int kt, int pc) {
;     char* st = lds_t + (kt % NSTG) * STAGE;
;     if (pc < 4)
;       __builtin_amdgcn_global_load_lds((const unsigned*)(ga + (size_t)(64 * pc) * lda + (size_t)kt * ksa), (unsigned __attribute__((address_space(3)))*)(st + pc * 8192), 16, 0, 0);
;     else
;       __builtin_amdgcn_global_load_lds((const unsigned*)(gb + (size_t)(64 * (pc - 4)) * ldb + (size_t)kt * ksb), (unsigned __attribute__((address_space(3)))*)(st + ABYTES + (pc - 4) * 8192), 16, 0, 0);
;   };
;   const int x = (r >> 1) & 7;
;   int xo[4];
; #pragma unroll
;   for (int s = 0; s < 4; ++s) xo[s] = (((2 * s + h) ^ x) << 4);
;   asm volatile("s_waitcnt vmcnt(0)" ::: "memory");
; #pragma unroll
;   for (int d = 0; d < DIST; ++d)
; #pragma unroll
;     for (int pc = 0; pc < NLD; ++pc) issue_piece(d, pc);
;   pre();
;   for (int kt = 0; kt < nk; ++kt) {
;     if (DIST == 2 && kt + 1 < nk) {
;       if (NLD == 6) asm volatile("s_waitcnt vmcnt(6)" ::: "memory");
;       else if (NLD == 5) asm volatile("s_waitcnt vmcnt(5)" ::: "memory");
;       else asm volatile("s_waitcnt vmcnt(8)" ::: "memory");
;     } else {
;       asm volatile("s_waitcnt vmcnt(0)" ::: "memory");
;     }
;     __builtin_amdgcn_s_barrier();
;     const bool pre = (kt + DIST < nk);
;     const char* base = smem + (kt % NSTG) * STAGE;
;     const char* pa = base + (wrow_act + r) * 128;
;     const char* pw = base + ABYTES + (wrow_w + r) * 128;
;     constexpr int NM = NI * MJ;
;     constexpr int PPS = (NLD + 1) / 2;
; #pragma unroll
;     for (int s = 0; s < 4; ++s) {
;       bf16x8 af[MJ], wf[NI];
; #pragma unroll
;       for (int j = 0; j < MJ; ++j) af[j] = *(const bf16x8*)(pa + j * 32 * 128 + xo[s]);
; #pragma unroll
;       for (int i = 0; i < NI; ++i) wf[i] = *(const bf16x8*)(pw + i * 32 * 128 + xo[s]);
; #pragma unroll
;       for (int m = 0; m < NM; ++m) {
;         const int i = m / MJ, j = m % MJ;
;         acc[i][j] = MFMA(wf[i], af[j], acc[i][j]);
.LBB0_353:
	s_ashr_i32 s53, s52, 31
	s_lshl_b64 s[0:1], s[52:53], 19
	s_add_u32 s0, s22, s0
	v_mov_b32_e32 v4, v147
	s_addc_u32 s1, s23, s1
	s_ashr_i32 s51, s50, 31
	s_lshl_b64 s[2:3], s[50:51], 19
	v_lshrrev_b32_e32 v0, 4, v4
	v_xor_b32_e32 v5, v0, v4
	v_ashrrev_i32_e32 v0, 3, v4
	s_add_u32 s2, s24, s2
	v_ashrrev_i32_e32 v1, 31, v0
	s_addc_u32 s3, s25, s3
	v_lshlrev_b64 v[0:1], 7, v[0:1]
	v_lshlrev_b32_e32 v5, 4, v5
	v_lshl_add_u32 v184, v4, 4, 0
	v_lshl_add_u64 v[2:3], s[2:3], 0, v[0:1]
	v_lshl_add_u64 v[0:1], s[0:1], 0, v[0:1]
	v_and_b32_e32 v144, 0x70, v5
	v_readfirstlane_b32 s15, v184
	v_add_u32_e32 v183, 0x2000, v184
	v_lshl_add_u64 v[130:131], v[0:1], 0, v[144:145]
	s_waitcnt vmcnt(0)
	s_mov_b32 m0, s15
	s_mov_b64 s[0:1], 0x2000
	v_readfirstlane_b32 s14, v183
	v_add_u32_e32 v182, 0x4000, v184
	global_load_lds_dwordx4 v[130:131], off
	v_lshl_add_u64 v[0:1], v[130:131], 0, s[0:1]
	s_mov_b32 m0, s14
	s_mov_b64 s[2:3], 0x4000
	v_readfirstlane_b32 s13, v182
	v_add_u32_e32 v181, 0x6000, v184
	v_add_u32_e32 v162, 0x8000, v184
	global_load_lds_dwordx4 v[0:1], off
	v_lshl_add_u64 v[0:1], v[130:131], 0, s[2:3]
	s_mov_b32 m0, s13
	s_mov_b64 s[4:5], 0x6000
	v_readfirstlane_b32 s12, v181
	global_load_lds_dwordx4 v[0:1], off
	v_lshl_add_u64 v[0:1], v[130:131], 0, s[4:5]
	s_mov_b32 m0, s12
	v_readfirstlane_b32 s11, v162
	v_add_u32_e32 v165, 0xa000, v184
	v_lshl_add_u64 v[128:129], v[2:3], 0, v[144:145]
	global_load_lds_dwordx4 v[0:1], off
	s_mov_b32 m0, s11
	v_readfirstlane_b32 s10, v165
	v_add_u32_e32 v164, 0xc000, v184
	global_load_lds_dwordx4 v[128:129], off
	v_lshl_add_u64 v[0:1], v[128:129], 0, s[0:1]
	s_mov_b32 m0, s10
	v_readfirstlane_b32 s9, v164
	v_add_u32_e32 v163, 0xe000, v184
	global_load_lds_dwordx4 v[0:1], off
	v_lshl_add_u64 v[0:1], v[128:129], 0, s[2:3]
	s_mov_b32 m0, s9
	v_readfirstlane_b32 s8, v163
	global_load_lds_dwordx4 v[0:1], off
	v_lshl_add_u64 v[0:1], v[128:129], 0, s[4:5]
	s_mov_b32 m0, s8
	v_bfe_u32 v17, v4, 1, 3
	global_load_lds_dwordx4 v[0:1], off
	v_lshrrev_b32_e32 v0, 5, v4
	v_bfe_u32 v16, v4, 5, 1
	v_bitop3_b32 v0, v0, v17, 1 bitop3:0x6c
	v_lshlrev_b32_e32 v142, 4, v0
	v_bitop3_b32 v0, v16, v17, 2 bitop3:0x36
	v_lshlrev_b32_e32 v143, 4, v0
	v_and_b32_e32 v0, 31, v4
	v_lshlrev_b32_e32 v144, 7, v0
	v_add_u32_e32 v151, v149, v144
	v_add_u32_e32 v132, v151, v142
	v_or_b32_e32 v4, v0, v146
	s_waitcnt vmcnt(0)
	s_barrier
	ds_read_b128 v[0:3], v132 offset:32768
	v_lshlrev_b32_e32 v152, 7, v4
	v_add_u32_e32 v153, 0, v152
	v_add_u32_e32 v136, v153, v142
	ds_read_b128 v[4:7], v136
	v_bitop3_b32 v8, v16, v17, 4 bitop3:0x36
	v_lshlrev_b32_e32 v185, 4, v8
	ds_read_b128 v[8:11], v136 offset:4096
	ds_read_b128 v[12:15], v132 offset:36864
	s_waitcnt lgkmcnt(0)
	v_mfma_f32_32x32x16_bf16 v[96:111], v[0:3], v[4:7], 0
	v_bitop3_b32 v16, v16, v17, 6 bitop3:0x36
	v_lshlrev_b32_e32 v210, 4, v16
	ds_read_b128 v[16:19], v132 offset:40960
	ds_read_b128 v[138:141], v132 offset:45056
	v_add_u32_e32 v155, 0x10000, v184
	v_lshl_add_u64 v[134:135], v[128:129], 0, s[34:35]
	v_add_u32_e32 v154, 0x18000, v184
	v_mfma_f32_32x32x16_bf16 v[64:79], v[0:3], v[8:11], 0
	v_readfirstlane_b32 s3, v155
	v_lshl_add_u64 v[0:1], v[130:131], 0, s[34:35]
	s_mov_b32 m0, s3
	s_nop 0
	global_load_lds_dwordx4 v[0:1], off
	v_mfma_f32_32x32x16_bf16 v[112:127], v[12:15], v[4:7], 0
	v_mfma_f32_32x32x16_bf16 v[80:95], v[12:15], v[8:11], 0
	v_add_u32_e32 v158, 0x12000, v184
	s_mov_b64 s[6:7], 0xa000
	v_readfirstlane_b32 s2, v158
	v_lshl_add_u64 v[0:1], v[130:131], 0, s[6:7]
	s_mov_b32 m0, s2
	s_nop 0
	global_load_lds_dwordx4 v[0:1], off
	s_waitcnt lgkmcnt(0)
	v_mfma_f32_32x32x16_bf16 v[48:63], v[16:19], v[4:7], 0
	v_mfma_f32_32x32x16_bf16 v[16:31], v[16:19], v[8:11], 0
	v_add_u32_e32 v157, 0x14000, v184
	v_lshl_add_u64 v[0:1], v[130:131], 0, s[60:61]
	v_readfirstlane_b32 s1, v157
	s_mov_b32 m0, s1
	s_nop 0
	global_load_lds_dwordx4 v[0:1], off
	v_mfma_f32_32x32x16_bf16 v[32:47], v[138:141], v[4:7], 0
	v_mfma_f32_32x32x16_bf16 v[0:15], v[138:141], v[8:11], 0
	v_add_u32_e32 v156, 0x16000, v184
	v_lshl_add_u64 v[138:139], v[130:131], 0, s[36:37]
	v_readfirstlane_b32 s0, v156
	s_mov_b32 m0, s0
	s_nop 0
	global_load_lds_dwordx4 v[138:139], off
	v_add_u32_e32 v133, v151, v143
	ds_read_b128 v[138:141], v133 offset:32768
	v_add_u32_e32 v137, v153, v143
	ds_read_b128 v[186:189], v137
	ds_read_b128 v[190:193], v137 offset:4096
	ds_read_b128 v[194:197], v133 offset:36864
	ds_read_b128 v[198:201], v133 offset:40960
	ds_read_b128 v[202:205], v133 offset:45056
	s_waitcnt lgkmcnt(0)
	v_mfma_f32_32x32x16_bf16 v[96:111], v[138:141], v[186:189], v[96:111]
	v_mfma_f32_32x32x16_bf16 v[64:79], v[138:141], v[190:193], v[64:79]
	v_readfirstlane_b32 s4, v154
	s_mov_b32 m0, s4
	s_nop 0
	global_load_lds_dwordx4 v[134:135], off
	v_mfma_f32_32x32x16_bf16 v[112:127], v[194:197], v[186:189], v[112:127]
	v_mfma_f32_32x32x16_bf16 v[80:95], v[194:197], v[190:193], v[80:95]
	v_add_u32_e32 v159, 0x1a000, v184
	v_lshl_add_u64 v[134:135], v[128:129], 0, s[6:7]
	v_readfirstlane_b32 s5, v159
	s_mov_b32 m0, s5
	s_nop 0
	global_load_lds_dwordx4 v[134:135], off
	v_mfma_f32_32x32x16_bf16 v[48:63], v[198:201], v[186:189], v[48:63]
	v_mfma_f32_32x32x16_bf16 v[16:31], v[198:201], v[190:193], v[16:31]
	v_add_u32_e32 v160, 0x1c000, v184
	v_lshl_add_u64 v[134:135], v[128:129], 0, s[60:61]
	v_readfirstlane_b32 s6, v160
	s_mov_b32 m0, s6
	s_nop 0
	global_load_lds_dwordx4 v[134:135], off
	v_mfma_f32_32x32x16_bf16 v[32:47], v[202:205], v[186:189], v[32:47]
	v_mfma_f32_32x32x16_bf16 v[0:15], v[202:205], v[190:193], v[0:15]
	v_add_u32_e32 v161, 0x1e000, v184
	v_lshl_add_u64 v[134:135], v[128:129], 0, s[36:37]
	v_readfirstlane_b32 s7, v161
	s_mov_b32 m0, s7
	s_nop 0
	global_load_lds_dwordx4 v[134:135], off
	v_add_u32_e32 v135, v151, v185
	ds_read_b128 v[212:215], v135 offset:32768
	v_add_u32_e32 v140, v153, v185
	ds_read_b128 v[216:219], v140
	ds_read_b128 v[220:223], v140 offset:4096
	ds_read_b128 v[224:227], v135 offset:36864
	v_add_u32_e32 v134, v151, v210
	v_add_u32_e32 v139, v153, v210
	s_waitcnt lgkmcnt(0)
; #define MFMA(a, b, c) __builtin_amdgcn_mfma_f32_32x32x16_bf16((a), (b), (c), 0, 0, 0)
;     ...
;   for (int kt = 0; kt < nk; ++kt) {
;     if (DIST == 2 && kt + 1 < nk) {
;       if (NLD == 6) asm volatile("s_waitcnt vmcnt(6)" ::: "memory");
;       else if (NLD == 5) asm volatile("s_waitcnt vmcnt(5)" ::: "memory");
;       else asm volatile("s_waitcnt vmcnt(8)" ::: "memory");
;     } else {
;       asm volatile("s_waitcnt vmcnt(0)" ::: "memory");
;     }
;     __builtin_amdgcn_s_barrier();
;     const bool pre = (kt + DIST < nk);
;     const char* base = smem + (kt % NSTG) * STAGE;
;     const char* pa = base + (wrow_act + r) * 128;
;     const char* pw = base + ABYTES + (wrow_w + r) * 128;
;     constexpr int NM = NI * MJ;
;     constexpr int PPS = (NLD + 1) / 2;
; #pragma unroll
;     for (int s = 0; s < 4; ++s) {
;       bf16x8 af[MJ], wf[NI];
; #pragma unroll
;       for (int j = 0; j < MJ; ++j) af[j] = *(const bf16x8*)(pa + j * 32 * 128 + xo[s]);
; #pragma unroll
;       for (int i = 0; i < NI; ++i) wf[i] = *(const bf16x8*)(pw + i * 32 * 128 + xo[s]);
; #pragma unroll
;       for (int m = 0; m < NM; ++m) {
;         const int i = m / MJ, j = m % MJ;
;         acc[i][j] = MFMA(wf[i], af[j], acc[i][j]);
;         if (s < 2 && NM >= PPS) {
;           constexpr int EVERY = (NM / PPS) > 0 ? (NM / PPS) : 1;
;           if ((m + 1) % EVERY == 0) {
;             const int pc = s * PPS + (m + 1) / EVERY - 1;
;             if ((m + 1) / EVERY <= PPS && pc < NLD) {
;               __builtin_amdgcn_sched_barrier(0);
;               if (pre) issue_piece(kt + DIST, pc);
;               __builtin_amdgcn_sched_barrier(0);
;             }
;           }
;         }
;         if (s < 2 && NM < PPS) {
;           const int slot = s * NM + m;
;           __builtin_amdgcn_sched_barrier(0);
; #pragma unroll
;           for (int pc = 0; pc < NLD; ++pc)
;             if ((pc * 2 * NM) / NLD == slot && pre) issue_piece(kt + DIST, pc);
;           __builtin_amdgcn_sched_barrier(0);
;         }
;       }
;     }
	ds_read_b128 v[186:189], v135 offset:40960
	ds_read_b128 v[198:201], v135 offset:45056
	v_mfma_f32_32x32x16_bf16 v[112:127], v[224:227], v[216:219], v[112:127]
	v_add_u32_e32 v141, v150, v144
	v_add_u32_e32 v138, v141, v142
	s_add_i32 s16, 0, 0x10000
	v_add_u32_e32 v211, s16, v152
	v_add_u32_e32 v142, v211, v142
	v_lshl_add_u64 v[152:153], v[128:129], 0, s[56:57]
	v_mfma_f32_32x32x16_bf16 v[96:111], v[212:215], v[216:219], v[96:111]
	v_mfma_f32_32x32x16_bf16 v[64:79], v[212:215], v[220:223], v[64:79]
	v_mfma_f32_32x32x16_bf16 v[80:95], v[224:227], v[220:223], v[80:95]
	s_waitcnt lgkmcnt(0)
	ds_read_b128 v[212:215], v134 offset:32768
	ds_read_b128 v[190:193], v139
	ds_read_b128 v[194:197], v139 offset:4096
	ds_read_b128 v[224:227], v134 offset:36864
	v_mfma_f32_32x32x16_bf16 v[48:63], v[186:189], v[216:219], v[48:63]
	v_mfma_f32_32x32x16_bf16 v[16:31], v[186:189], v[220:223], v[16:31]
	v_mfma_f32_32x32x16_bf16 v[32:47], v[198:201], v[216:219], v[32:47]
	v_mfma_f32_32x32x16_bf16 v[0:15], v[198:201], v[220:223], v[0:15]
	s_waitcnt lgkmcnt(0)
	ds_read_b128 v[186:189], v134 offset:40960
	ds_read_b128 v[198:201], v134 offset:45056
	v_mfma_f32_32x32x16_bf16 v[96:111], v[212:215], v[190:193], v[96:111]
	v_mfma_f32_32x32x16_bf16 v[64:79], v[212:215], v[194:197], v[64:79]
	v_mfma_f32_32x32x16_bf16 v[112:127], v[224:227], v[190:193], v[112:127]
	v_mfma_f32_32x32x16_bf16 v[80:95], v[224:227], v[194:197], v[80:95]
	s_waitcnt vmcnt(0)
	s_barrier
	s_waitcnt lgkmcnt(0)
	v_mfma_f32_32x32x16_bf16 v[48:63], v[186:189], v[190:193], v[48:63]
	v_mfma_f32_32x32x16_bf16 v[16:31], v[186:189], v[194:197], v[16:31]
	ds_read_b128 v[186:189], v138
	ds_read_b128 v[216:219], v142
	ds_read_b128 v[220:223], v142 offset:4096
	ds_read_b128 v[224:227], v138 offset:4096
	ds_read_b128 v[228:231], v138 offset:8192
	ds_read_b128 v[206:209], v138 offset:12288
	v_mfma_f32_32x32x16_bf16 v[32:47], v[198:201], v[190:193], v[32:47]
	v_mfma_f32_32x32x16_bf16 v[0:15], v[198:201], v[194:197], v[0:15]
	s_waitcnt lgkmcnt(0)
	v_mfma_f32_32x32x16_bf16 v[96:111], v[186:189], v[216:219], v[96:111]
	v_mfma_f32_32x32x16_bf16 v[64:79], v[186:189], v[220:223], v[64:79]
	v_lshl_add_u64 v[186:187], v[130:131], 0, s[56:57]
	s_mov_b32 m0, s15
	s_nop 0
	global_load_lds_dwordx4 v[186:187], off
	v_mfma_f32_32x32x16_bf16 v[112:127], v[224:227], v[216:219], v[112:127]
	v_mfma_f32_32x32x16_bf16 v[80:95], v[224:227], v[220:223], v[80:95]
	s_mov_b64 s[16:17], 0x12000
	v_lshl_add_u64 v[186:187], v[130:131], 0, s[16:17]
	s_mov_b32 m0, s14
	s_nop 0
	global_load_lds_dwordx4 v[186:187], off
	v_mfma_f32_32x32x16_bf16 v[48:63], v[228:231], v[216:219], v[48:63]
	v_mfma_f32_32x32x16_bf16 v[16:31], v[228:231], v[220:223], v[16:31]
	s_mov_b64 s[18:19], 0x14000
	v_lshl_add_u64 v[186:187], v[130:131], 0, s[18:19]
	s_mov_b32 m0, s13
	s_nop 0
	global_load_lds_dwordx4 v[186:187], off
	v_mfma_f32_32x32x16_bf16 v[32:47], v[206:209], v[216:219], v[32:47]
	v_mfma_f32_32x32x16_bf16 v[0:15], v[206:209], v[220:223], v[0:15]
	s_mov_b64 s[20:21], 0x16000
	v_lshl_add_u64 v[186:187], v[130:131], 0, s[20:21]
	s_mov_b32 m0, s12
	s_nop 0
	global_load_lds_dwordx4 v[186:187], off
	v_add_u32_e32 v144, v141, v143
	ds_read_b128 v[186:189], v144
	v_add_u32_e32 v151, v211, v143
	ds_read_b128 v[190:193], v151
	ds_read_b128 v[194:197], v151 offset:4096
	ds_read_b128 v[198:201], v144 offset:4096
	ds_read_b128 v[202:205], v144 offset:8192
	ds_read_b128 v[232:235], v144 offset:12288
	s_waitcnt lgkmcnt(0)
	v_mfma_f32_32x32x16_bf16 v[96:111], v[186:189], v[190:193], v[96:111]
	v_mfma_f32_32x32x16_bf16 v[64:79], v[186:189], v[194:197], v[64:79]
	s_mov_b32 m0, s11
	s_nop 0
	global_load_lds_dwordx4 v[152:153], off
	v_mfma_f32_32x32x16_bf16 v[112:127], v[198:201], v[190:193], v[112:127]
	v_mfma_f32_32x32x16_bf16 v[80:95], v[198:201], v[194:197], v[80:95]
	v_lshl_add_u64 v[152:153], v[128:129], 0, s[16:17]
	s_mov_b32 m0, s10
	s_nop 0
	global_load_lds_dwordx4 v[152:153], off
	v_mfma_f32_32x32x16_bf16 v[48:63], v[202:205], v[190:193], v[48:63]
	v_mfma_f32_32x32x16_bf16 v[16:31], v[202:205], v[194:197], v[16:31]
	v_lshl_add_u64 v[152:153], v[128:129], 0, s[18:19]
	s_mov_b32 m0, s9
	s_nop 0
	global_load_lds_dwordx4 v[152:153], off
	v_mfma_f32_32x32x16_bf16 v[32:47], v[232:235], v[190:193], v[32:47]
	v_mfma_f32_32x32x16_bf16 v[0:15], v[232:235], v[194:197], v[0:15]
	v_lshl_add_u64 v[152:153], v[128:129], 0, s[20:21]
	s_mov_b32 m0, s8
	s_nop 0
	global_load_lds_dwordx4 v[152:153], off
	v_add_u32_e32 v143, v141, v185
	ds_read_b128 v[212:215], v143
	v_add_u32_e32 v153, v211, v185
	ds_read_b128 v[216:219], v153
	ds_read_b128 v[220:223], v153 offset:4096
	ds_read_b128 v[224:227], v143 offset:4096
	v_add_u32_e32 v141, v141, v210
	v_add_u32_e32 v152, v211, v210
	s_waitcnt lgkmcnt(0)
	ds_read_b128 v[186:189], v143 offset:8192
	ds_read_b128 v[198:201], v143 offset:12288
	v_mfma_f32_32x32x16_bf16 v[112:127], v[224:227], v[216:219], v[112:127]
	v_lshl_add_u64 v[210:211], v[128:129], 0, s[58:59]
	v_mfma_f32_32x32x16_bf16 v[96:111], v[212:215], v[216:219], v[96:111]
	v_mfma_f32_32x32x16_bf16 v[64:79], v[212:215], v[220:223], v[64:79]
	v_mfma_f32_32x32x16_bf16 v[80:95], v[224:227], v[220:223], v[80:95]
	s_waitcnt lgkmcnt(0)
	ds_read_b128 v[212:215], v141
	ds_read_b128 v[190:193], v152
	ds_read_b128 v[194:197], v152 offset:4096
	ds_read_b128 v[224:227], v141 offset:4096
	v_mfma_f32_32x32x16_bf16 v[48:63], v[186:189], v[216:219], v[48:63]
	v_mfma_f32_32x32x16_bf16 v[16:31], v[186:189], v[220:223], v[16:31]
	v_mfma_f32_32x32x16_bf16 v[32:47], v[198:201], v[216:219], v[32:47]
	v_mfma_f32_32x32x16_bf16 v[0:15], v[198:201], v[220:223], v[0:15]
	s_waitcnt lgkmcnt(0)
	ds_read_b128 v[186:189], v141 offset:8192
	ds_read_b128 v[198:201], v141 offset:12288
	v_mfma_f32_32x32x16_bf16 v[96:111], v[212:215], v[190:193], v[96:111]
	v_mfma_f32_32x32x16_bf16 v[64:79], v[212:215], v[194:197], v[64:79]
	v_mfma_f32_32x32x16_bf16 v[112:127], v[224:227], v[190:193], v[112:127]
	v_mfma_f32_32x32x16_bf16 v[80:95], v[224:227], v[194:197], v[80:95]
	s_waitcnt vmcnt(0)
	s_barrier
; #define MFMA(a, b, c) __builtin_amdgcn_mfma_f32_32x32x16_bf16((a), (b), (c), 0, 0, 0)
;     ...
;   for (int kt = 0; kt < nk; ++kt) {
;     if (DIST == 2 && kt + 1 < nk) {
;       if (NLD == 6) asm volatile("s_waitcnt vmcnt(6)" ::: "memory");
;       else if (NLD == 5) asm volatile("s_waitcnt vmcnt(5)" ::: "memory");
;       else asm volatile("s_waitcnt vmcnt(8)" ::: "memory");
;     } else {
;       asm volatile("s_waitcnt vmcnt(0)" ::: "memory");
;     }
;     __builtin_amdgcn_s_barrier();
;     const bool pre = (kt + DIST < nk);
;     const char* base = smem + (kt % NSTG) * STAGE;
;     const char* pa = base + (wrow_act + r) * 128;
;     const char* pw = base + ABYTES + (wrow_w + r) * 128;
;     constexpr int NM = NI * MJ;
;     constexpr int PPS = (NLD + 1) / 2;
; #pragma unroll
;     for (int s = 0; s < 4; ++s) {
;       bf16x8 af[MJ], wf[NI];
; #pragma unroll
;       for (int j = 0; j < MJ; ++j) af[j] = *(const bf16x8*)(pa + j * 32 * 128 + xo[s]);
; #pragma unroll
;       for (int i = 0; i < NI; ++i) wf[i] = *(const bf16x8*)(pw + i * 32 * 128 + xo[s]);
; #pragma unroll
;       for (int m = 0; m < NM; ++m) {
;         const int i = m / MJ, j = m % MJ;
;         acc[i][j] = MFMA(wf[i], af[j], acc[i][j]);
;         if (s < 2 && NM >= PPS) {
;           constexpr int EVERY = (NM / PPS) > 0 ? (NM / PPS) : 1;
;           if ((m + 1) % EVERY == 0) {
;             const int pc = s * PPS + (m + 1) / EVERY - 1;
;             if ((m + 1) / EVERY <= PPS && pc < NLD) {
;               __builtin_amdgcn_sched_barrier(0);
;               if (pre) issue_piece(kt + DIST, pc);
;               __builtin_amdgcn_sched_barrier(0);
;             }
;           }
;         }
;         if (s < 2 && NM < PPS) {
;           const int slot = s * NM + m;
;           __builtin_amdgcn_sched_barrier(0);
; #pragma unroll
;           for (int pc = 0; pc < NLD; ++pc)
;             if ((pc * 2 * NM) / NLD == slot && pre) issue_piece(kt + DIST, pc);
;           __builtin_amdgcn_sched_barrier(0);
;         }
;       }
;     }
	s_waitcnt lgkmcnt(0)
	v_mfma_f32_32x32x16_bf16 v[48:63], v[186:189], v[190:193], v[48:63]
	v_mfma_f32_32x32x16_bf16 v[16:31], v[186:189], v[194:197], v[16:31]
	ds_read_b128 v[186:189], v132 offset:32768
	ds_read_b128 v[216:219], v136
	ds_read_b128 v[220:223], v136 offset:4096
	ds_read_b128 v[224:227], v132 offset:36864
	ds_read_b128 v[228:231], v132 offset:40960
	ds_read_b128 v[206:209], v132 offset:45056
	v_mfma_f32_32x32x16_bf16 v[32:47], v[198:201], v[190:193], v[32:47]
	v_mfma_f32_32x32x16_bf16 v[0:15], v[198:201], v[194:197], v[0:15]
	s_waitcnt lgkmcnt(0)
	v_mfma_f32_32x32x16_bf16 v[96:111], v[186:189], v[216:219], v[96:111]
	v_mfma_f32_32x32x16_bf16 v[64:79], v[186:189], v[220:223], v[64:79]
	v_lshl_add_u64 v[186:187], v[130:131], 0, s[58:59]
	s_mov_b32 m0, s3
	s_nop 0
	global_load_lds_dwordx4 v[186:187], off
	v_mfma_f32_32x32x16_bf16 v[112:127], v[224:227], v[216:219], v[112:127]
	v_mfma_f32_32x32x16_bf16 v[80:95], v[224:227], v[220:223], v[80:95]
	s_mov_b64 s[16:17], 0x1a000
	v_lshl_add_u64 v[186:187], v[130:131], 0, s[16:17]
	s_mov_b32 m0, s2
	s_nop 0
	global_load_lds_dwordx4 v[186:187], off
	v_mfma_f32_32x32x16_bf16 v[48:63], v[228:231], v[216:219], v[48:63]
	v_mfma_f32_32x32x16_bf16 v[16:31], v[228:231], v[220:223], v[16:31]
	s_mov_b64 s[18:19], 0x1c000
	v_lshl_add_u64 v[186:187], v[130:131], 0, s[18:19]
	s_mov_b32 m0, s1
	s_nop 0
	global_load_lds_dwordx4 v[186:187], off
	v_mfma_f32_32x32x16_bf16 v[32:47], v[206:209], v[216:219], v[32:47]
	v_mfma_f32_32x32x16_bf16 v[0:15], v[206:209], v[220:223], v[0:15]
	s_mov_b64 s[20:21], 0x1e000
	v_lshl_add_u64 v[186:187], v[130:131], 0, s[20:21]
	s_mov_b32 m0, s0
	s_nop 0
	global_load_lds_dwordx4 v[186:187], off
	ds_read_b128 v[186:189], v133 offset:32768
	ds_read_b128 v[190:193], v137
	ds_read_b128 v[194:197], v137 offset:4096
	ds_read_b128 v[198:201], v133 offset:36864
	ds_read_b128 v[202:205], v133 offset:40960
	ds_read_b128 v[232:235], v133 offset:45056
	s_waitcnt lgkmcnt(0)
	ds_read_b128 v[212:215], v135 offset:32768
	ds_read_b128 v[216:219], v140
	ds_read_b128 v[220:223], v140 offset:4096
	ds_read_b128 v[224:227], v135 offset:36864
	v_mfma_f32_32x32x16_bf16 v[96:111], v[186:189], v[190:193], v[96:111]
	v_mfma_f32_32x32x16_bf16 v[64:79], v[186:189], v[194:197], v[64:79]
	s_mov_b32 m0, s4
	s_nop 0
	global_load_lds_dwordx4 v[210:211], off
	v_mfma_f32_32x32x16_bf16 v[112:127], v[198:201], v[190:193], v[112:127]
	v_mfma_f32_32x32x16_bf16 v[80:95], v[198:201], v[194:197], v[80:95]
	v_lshl_add_u64 v[186:187], v[128:129], 0, s[16:17]
	s_mov_b32 m0, s5
	s_nop 0
	global_load_lds_dwordx4 v[186:187], off
	v_mfma_f32_32x32x16_bf16 v[48:63], v[202:205], v[190:193], v[48:63]
	v_mfma_f32_32x32x16_bf16 v[16:31], v[202:205], v[194:197], v[16:31]
	v_lshl_add_u64 v[186:187], v[128:129], 0, s[18:19]
	s_mov_b32 m0, s6
	s_nop 0
	global_load_lds_dwordx4 v[186:187], off
	v_mfma_f32_32x32x16_bf16 v[32:47], v[232:235], v[190:193], v[32:47]
	v_mfma_f32_32x32x16_bf16 v[0:15], v[232:235], v[194:197], v[0:15]
	v_lshl_add_u64 v[186:187], v[128:129], 0, s[20:21]
	s_mov_b32 m0, s7
	s_nop 0
	global_load_lds_dwordx4 v[186:187], off
	s_mov_b64 s[16:17], 0x20000
	v_lshl_add_u64 v[210:211], v[128:129], 0, s[16:17]
	s_waitcnt lgkmcnt(0)
	ds_read_b128 v[186:189], v135 offset:40960
	ds_read_b128 v[198:201], v135 offset:45056
	v_mfma_f32_32x32x16_bf16 v[96:111], v[212:215], v[216:219], v[96:111]
	v_mfma_f32_32x32x16_bf16 v[64:79], v[212:215], v[220:223], v[64:79]
	v_mfma_f32_32x32x16_bf16 v[112:127], v[224:227], v[216:219], v[112:127]
	v_mfma_f32_32x32x16_bf16 v[80:95], v[224:227], v[220:223], v[80:95]
	s_waitcnt lgkmcnt(0)
	ds_read_b128 v[212:215], v134 offset:32768
	ds_read_b128 v[190:193], v139
	ds_read_b128 v[194:197], v139 offset:4096
	ds_read_b128 v[224:227], v134 offset:36864
	v_mfma_f32_32x32x16_bf16 v[48:63], v[186:189], v[216:219], v[48:63]
	v_mfma_f32_32x32x16_bf16 v[16:31], v[186:189], v[220:223], v[16:31]
	v_mfma_f32_32x32x16_bf16 v[32:47], v[198:201], v[216:219], v[32:47]
	v_mfma_f32_32x32x16_bf16 v[0:15], v[198:201], v[220:223], v[0:15]
	s_waitcnt lgkmcnt(0)
	ds_read_b128 v[186:189], v134 offset:40960
	ds_read_b128 v[198:201], v134 offset:45056
	v_mfma_f32_32x32x16_bf16 v[96:111], v[212:215], v[190:193], v[96:111]
	v_mfma_f32_32x32x16_bf16 v[64:79], v[212:215], v[194:197], v[64:79]
	v_mfma_f32_32x32x16_bf16 v[112:127], v[224:227], v[190:193], v[112:127]
	v_mfma_f32_32x32x16_bf16 v[80:95], v[224:227], v[194:197], v[80:95]
	s_waitcnt vmcnt(0)
	s_barrier
; #define MFMA(a, b, c) __builtin_amdgcn_mfma_f32_32x32x16_bf16((a), (b), (c), 0, 0, 0)
;     ...
;   for (int kt = 0; kt < nk; ++kt) {
;     if (DIST == 2 && kt + 1 < nk) {
;       if (NLD == 6) asm volatile("s_waitcnt vmcnt(6)" ::: "memory");
;       else if (NLD == 5) asm volatile("s_waitcnt vmcnt(5)" ::: "memory");
;       else asm volatile("s_waitcnt vmcnt(8)" ::: "memory");
;     } else {
;       asm volatile("s_waitcnt vmcnt(0)" ::: "memory");
;     }
;     __builtin_amdgcn_s_barrier();
;     const bool pre = (kt + DIST < nk);
;     const char* base = smem + (kt % NSTG) * STAGE;
;     const char* pa = base + (wrow_act + r) * 128;
;     const char* pw = base + ABYTES + (wrow_w + r) * 128;
;     constexpr int NM = NI * MJ;
;     constexpr int PPS = (NLD + 1) / 2;
; #pragma unroll
;     for (int s = 0; s < 4; ++s) {
;       bf16x8 af[MJ], wf[NI];
; #pragma unroll
;       for (int j = 0; j < MJ; ++j) af[j] = *(const bf16x8*)(pa + j * 32 * 128 + xo[s]);
; #pragma unroll
;       for (int i = 0; i < NI; ++i) wf[i] = *(const bf16x8*)(pw + i * 32 * 128 + xo[s]);
; #pragma unroll
;       for (int m = 0; m < NM; ++m) {
;         const int i = m / MJ, j = m % MJ;
;         acc[i][j] = MFMA(wf[i], af[j], acc[i][j]);
;         if (s < 2 && NM >= PPS) {
;           constexpr int EVERY = (NM / PPS) > 0 ? (NM / PPS) : 1;
;           if ((m + 1) % EVERY == 0) {
;             const int pc = s * PPS + (m + 1) / EVERY - 1;
;             if ((m + 1) / EVERY <= PPS && pc < NLD) {
;               __builtin_amdgcn_sched_barrier(0);
;               if (pre) issue_piece(kt + DIST, pc);
;               __builtin_amdgcn_sched_barrier(0);
;             }
;           }
;         }
;         if (s < 2 && NM < PPS) {
;           const int slot = s * NM + m;
;           __builtin_amdgcn_sched_barrier(0);
; #pragma unroll
;           for (int pc = 0; pc < NLD; ++pc)
;             if ((pc * 2 * NM) / NLD == slot && pre) issue_piece(kt + DIST, pc);
;           __builtin_amdgcn_sched_barrier(0);
;         }
;       }
;     }
	s_waitcnt lgkmcnt(0)
	v_mfma_f32_32x32x16_bf16 v[48:63], v[186:189], v[190:193], v[48:63]
	v_mfma_f32_32x32x16_bf16 v[16:31], v[186:189], v[194:197], v[16:31]
	ds_read_b128 v[186:189], v138
	ds_read_b128 v[216:219], v142
	ds_read_b128 v[220:223], v142 offset:4096
	ds_read_b128 v[224:227], v138 offset:4096
	ds_read_b128 v[228:231], v138 offset:8192
	ds_read_b128 v[206:209], v138 offset:12288
	v_mfma_f32_32x32x16_bf16 v[32:47], v[198:201], v[190:193], v[32:47]
	v_mfma_f32_32x32x16_bf16 v[0:15], v[198:201], v[194:197], v[0:15]
	s_waitcnt lgkmcnt(0)
	v_mfma_f32_32x32x16_bf16 v[96:111], v[186:189], v[216:219], v[96:111]
	v_mfma_f32_32x32x16_bf16 v[64:79], v[186:189], v[220:223], v[64:79]
	v_lshl_add_u64 v[186:187], v[130:131], 0, s[16:17]
	s_mov_b32 m0, s15
	s_nop 0
	global_load_lds_dwordx4 v[186:187], off
	v_mfma_f32_32x32x16_bf16 v[112:127], v[224:227], v[216:219], v[112:127]
	v_mfma_f32_32x32x16_bf16 v[80:95], v[224:227], v[220:223], v[80:95]
	s_mov_b64 s[16:17], 0x22000
	v_lshl_add_u64 v[186:187], v[130:131], 0, s[16:17]
	s_mov_b32 m0, s14
	s_nop 0
	global_load_lds_dwordx4 v[186:187], off
	v_mfma_f32_32x32x16_bf16 v[48:63], v[228:231], v[216:219], v[48:63]
	v_mfma_f32_32x32x16_bf16 v[16:31], v[228:231], v[220:223], v[16:31]
	v_lshl_add_u64 v[186:187], v[130:131], 0, s[62:63]
	s_mov_b32 m0, s13
	s_nop 0
	global_load_lds_dwordx4 v[186:187], off
	v_mfma_f32_32x32x16_bf16 v[32:47], v[206:209], v[216:219], v[32:47]
	v_mfma_f32_32x32x16_bf16 v[0:15], v[206:209], v[220:223], v[0:15]
	s_mov_b64 s[14:15], 0x26000
	v_lshl_add_u64 v[186:187], v[130:131], 0, s[14:15]
	s_mov_b32 m0, s12
	s_nop 0
	global_load_lds_dwordx4 v[186:187], off
	ds_read_b128 v[186:189], v144
	ds_read_b128 v[190:193], v151
	ds_read_b128 v[194:197], v151 offset:4096
	ds_read_b128 v[198:201], v144 offset:4096
	ds_read_b128 v[202:205], v144 offset:8192
	ds_read_b128 v[232:235], v144 offset:12288
	s_waitcnt lgkmcnt(0)
	ds_read_b128 v[212:215], v143
	ds_read_b128 v[216:219], v153
	ds_read_b128 v[220:223], v153 offset:4096
	ds_read_b128 v[224:227], v143 offset:4096
	v_mfma_f32_32x32x16_bf16 v[96:111], v[186:189], v[190:193], v[96:111]
	v_mfma_f32_32x32x16_bf16 v[64:79], v[186:189], v[194:197], v[64:79]
	s_mov_b32 m0, s11
	s_nop 0
	global_load_lds_dwordx4 v[210:211], off
	v_mfma_f32_32x32x16_bf16 v[112:127], v[198:201], v[190:193], v[112:127]
	v_mfma_f32_32x32x16_bf16 v[80:95], v[198:201], v[194:197], v[80:95]
	v_lshl_add_u64 v[186:187], v[128:129], 0, s[16:17]
	s_mov_b32 m0, s10
	s_nop 0
	global_load_lds_dwordx4 v[186:187], off
	v_mfma_f32_32x32x16_bf16 v[48:63], v[202:205], v[190:193], v[48:63]
	v_mfma_f32_32x32x16_bf16 v[16:31], v[202:205], v[194:197], v[16:31]
	v_lshl_add_u64 v[186:187], v[128:129], 0, s[62:63]
	s_mov_b32 m0, s9
	s_nop 0
	global_load_lds_dwordx4 v[186:187], off
	v_mfma_f32_32x32x16_bf16 v[32:47], v[232:235], v[190:193], v[32:47]
	v_mfma_f32_32x32x16_bf16 v[0:15], v[232:235], v[194:197], v[0:15]
	v_lshl_add_u64 v[186:187], v[128:129], 0, s[14:15]
	s_mov_b32 m0, s8
	s_nop 0
	global_load_lds_dwordx4 v[186:187], off
	s_mov_b64 s[8:9], 0x28000
	v_lshl_add_u64 v[210:211], v[128:129], 0, s[8:9]
	s_waitcnt lgkmcnt(0)
	ds_read_b128 v[186:189], v143 offset:8192
	ds_read_b128 v[198:201], v143 offset:12288
	v_mfma_f32_32x32x16_bf16 v[96:111], v[212:215], v[216:219], v[96:111]
	v_mfma_f32_32x32x16_bf16 v[64:79], v[212:215], v[220:223], v[64:79]
	v_mfma_f32_32x32x16_bf16 v[112:127], v[224:227], v[216:219], v[112:127]
	v_mfma_f32_32x32x16_bf16 v[80:95], v[224:227], v[220:223], v[80:95]
	s_waitcnt lgkmcnt(0)
	ds_read_b128 v[212:215], v141
	ds_read_b128 v[190:193], v152
	ds_read_b128 v[194:197], v152 offset:4096
	ds_read_b128 v[224:227], v141 offset:4096
	v_mfma_f32_32x32x16_bf16 v[48:63], v[186:189], v[216:219], v[48:63]
	v_mfma_f32_32x32x16_bf16 v[16:31], v[186:189], v[220:223], v[16:31]
	v_mfma_f32_32x32x16_bf16 v[32:47], v[198:201], v[216:219], v[32:47]
	v_mfma_f32_32x32x16_bf16 v[0:15], v[198:201], v[220:223], v[0:15]
	s_waitcnt lgkmcnt(0)
	ds_read_b128 v[186:189], v141 offset:8192
	ds_read_b128 v[198:201], v141 offset:12288
	v_mfma_f32_32x32x16_bf16 v[96:111], v[212:215], v[190:193], v[96:111]
	v_mfma_f32_32x32x16_bf16 v[64:79], v[212:215], v[194:197], v[64:79]
	v_mfma_f32_32x32x16_bf16 v[112:127], v[224:227], v[190:193], v[112:127]
	v_mfma_f32_32x32x16_bf16 v[80:95], v[224:227], v[194:197], v[80:95]
	s_waitcnt vmcnt(0)
	s_barrier
; #define MFMA(a, b, c) __builtin_amdgcn_mfma_f32_32x32x16_bf16((a), (b), (c), 0, 0, 0)
;     ...
;   for (int kt = 0; kt < nk; ++kt) {
;     if (DIST == 2 && kt + 1 < nk) {
;       if (NLD == 6) asm volatile("s_waitcnt vmcnt(6)" ::: "memory");
;       else if (NLD == 5) asm volatile("s_waitcnt vmcnt(5)" ::: "memory");
;       else asm volatile("s_waitcnt vmcnt(8)" ::: "memory");
;     } else {
;       asm volatile("s_waitcnt vmcnt(0)" ::: "memory");
;     }
;     __builtin_amdgcn_s_barrier();
;     const bool pre = (kt + DIST < nk);
;     const char* base = smem + (kt % NSTG) * STAGE;
;     const char* pa = base + (wrow_act + r) * 128;
;     const char* pw = base + ABYTES + (wrow_w + r) * 128;
;     constexpr int NM = NI * MJ;
;     constexpr int PPS = (NLD + 1) / 2;
; #pragma unroll
;     for (int s = 0; s < 4; ++s) {
;       bf16x8 af[MJ], wf[NI];
; #pragma unroll
;       for (int j = 0; j < MJ; ++j) af[j] = *(const bf16x8*)(pa + j * 32 * 128 + xo[s]);
; #pragma unroll
;       for (int i = 0; i < NI; ++i) wf[i] = *(const bf16x8*)(pw + i * 32 * 128 + xo[s]);
; #pragma unroll
;       for (int m = 0; m < NM; ++m) {
;         const int i = m / MJ, j = m % MJ;
;         acc[i][j] = MFMA(wf[i], af[j], acc[i][j]);
;         if (s < 2 && NM >= PPS) {
;           constexpr int EVERY = (NM / PPS) > 0 ? (NM / PPS) : 1;
;           if ((m + 1) % EVERY == 0) {
;             const int pc = s * PPS + (m + 1) / EVERY - 1;
;             if ((m + 1) / EVERY <= PPS && pc < NLD) {
;               __builtin_amdgcn_sched_barrier(0);
;               if (pre) issue_piece(kt + DIST, pc);
;               __builtin_amdgcn_sched_barrier(0);
;             }
;           }
;         }
;         if (s < 2 && NM < PPS) {
;           const int slot = s * NM + m;
;           __builtin_amdgcn_sched_barrier(0);
; #pragma unroll
;           for (int pc = 0; pc < NLD; ++pc)
;             if ((pc * 2 * NM) / NLD == slot && pre) issue_piece(kt + DIST, pc);
;           __builtin_amdgcn_sched_barrier(0);
;         }
;       }
;     }
	s_waitcnt lgkmcnt(0)
	v_mfma_f32_32x32x16_bf16 v[48:63], v[186:189], v[190:193], v[48:63]
	v_mfma_f32_32x32x16_bf16 v[16:31], v[186:189], v[194:197], v[16:31]
	ds_read_b128 v[186:189], v132 offset:32768
	ds_read_b128 v[216:219], v136
	ds_read_b128 v[220:223], v136 offset:4096
	ds_read_b128 v[224:227], v132 offset:36864
	ds_read_b128 v[228:231], v132 offset:40960
	ds_read_b128 v[206:209], v132 offset:45056
	v_mfma_f32_32x32x16_bf16 v[32:47], v[198:201], v[190:193], v[32:47]
	v_mfma_f32_32x32x16_bf16 v[0:15], v[198:201], v[194:197], v[0:15]
	s_waitcnt lgkmcnt(0)
	v_mfma_f32_32x32x16_bf16 v[96:111], v[186:189], v[216:219], v[96:111]
	v_mfma_f32_32x32x16_bf16 v[64:79], v[186:189], v[220:223], v[64:79]
	v_lshl_add_u64 v[186:187], v[130:131], 0, s[8:9]
	s_mov_b32 m0, s3
	s_nop 0
	global_load_lds_dwordx4 v[186:187], off
	v_mfma_f32_32x32x16_bf16 v[112:127], v[224:227], v[216:219], v[112:127]
	v_mfma_f32_32x32x16_bf16 v[80:95], v[224:227], v[220:223], v[80:95]
	s_mov_b64 s[8:9], 0x2a000
	v_lshl_add_u64 v[186:187], v[130:131], 0, s[8:9]
	s_mov_b32 m0, s2
	s_nop 0
	global_load_lds_dwordx4 v[186:187], off
	v_mfma_f32_32x32x16_bf16 v[48:63], v[228:231], v[216:219], v[48:63]
	v_mfma_f32_32x32x16_bf16 v[16:31], v[228:231], v[220:223], v[16:31]
	s_mov_b64 s[2:3], 0x2c000
	v_lshl_add_u64 v[186:187], v[130:131], 0, s[2:3]
	s_mov_b32 m0, s1
	s_nop 0
	global_load_lds_dwordx4 v[186:187], off
	v_mfma_f32_32x32x16_bf16 v[32:47], v[206:209], v[216:219], v[32:47]
	v_mfma_f32_32x32x16_bf16 v[0:15], v[206:209], v[220:223], v[0:15]
	s_mov_b64 s[10:11], 0x2e000
	v_lshl_add_u64 v[186:187], v[130:131], 0, s[10:11]
	s_mov_b32 m0, s0
	s_nop 0
	global_load_lds_dwordx4 v[186:187], off
	ds_read_b128 v[186:189], v133 offset:32768
	ds_read_b128 v[190:193], v137
	ds_read_b128 v[194:197], v137 offset:4096
	ds_read_b128 v[198:201], v133 offset:36864
	ds_read_b128 v[202:205], v133 offset:40960
	ds_read_b128 v[232:235], v133 offset:45056
	s_waitcnt lgkmcnt(0)
	ds_read_b128 v[212:215], v135 offset:32768
	ds_read_b128 v[216:219], v140
	ds_read_b128 v[220:223], v140 offset:4096
	ds_read_b128 v[224:227], v135 offset:36864
	v_mfma_f32_32x32x16_bf16 v[96:111], v[186:189], v[190:193], v[96:111]
	v_mfma_f32_32x32x16_bf16 v[64:79], v[186:189], v[194:197], v[64:79]
	s_mov_b32 m0, s4
	s_nop 0
	global_load_lds_dwordx4 v[210:211], off
	v_mfma_f32_32x32x16_bf16 v[112:127], v[198:201], v[190:193], v[112:127]
	v_mfma_f32_32x32x16_bf16 v[80:95], v[198:201], v[194:197], v[80:95]
	v_lshl_add_u64 v[186:187], v[128:129], 0, s[8:9]
	s_mov_b32 m0, s5
	s_nop 0
	global_load_lds_dwordx4 v[186:187], off
	v_mfma_f32_32x32x16_bf16 v[48:63], v[202:205], v[190:193], v[48:63]
	v_mfma_f32_32x32x16_bf16 v[16:31], v[202:205], v[194:197], v[16:31]
	v_lshl_add_u64 v[186:187], v[128:129], 0, s[2:3]
	s_mov_b32 m0, s6
	s_nop 0
	global_load_lds_dwordx4 v[186:187], off
	v_mfma_f32_32x32x16_bf16 v[32:47], v[232:235], v[190:193], v[32:47]
	v_mfma_f32_32x32x16_bf16 v[0:15], v[232:235], v[194:197], v[0:15]
	v_lshl_add_u64 v[186:187], v[128:129], 0, s[10:11]
	s_mov_b32 m0, s7
	s_nop 0
	global_load_lds_dwordx4 v[186:187], off
	s_mov_b64 s[0:1], 0x30000
	v_lshl_add_u64 v[210:211], v[128:129], 0, s[0:1]
	s_waitcnt lgkmcnt(0)
	ds_read_b128 v[186:189], v135 offset:40960
	ds_read_b128 v[198:201], v135 offset:45056
	v_mfma_f32_32x32x16_bf16 v[96:111], v[212:215], v[216:219], v[96:111]
	v_mfma_f32_32x32x16_bf16 v[64:79], v[212:215], v[220:223], v[64:79]
	v_mfma_f32_32x32x16_bf16 v[112:127], v[224:227], v[216:219], v[112:127]
	v_mfma_f32_32x32x16_bf16 v[80:95], v[224:227], v[220:223], v[80:95]
	s_waitcnt lgkmcnt(0)
	ds_read_b128 v[212:215], v134 offset:32768
	ds_read_b128 v[190:193], v139
	ds_read_b128 v[194:197], v139 offset:4096
	ds_read_b128 v[224:227], v134 offset:36864
	v_mfma_f32_32x32x16_bf16 v[48:63], v[186:189], v[216:219], v[48:63]
	v_mfma_f32_32x32x16_bf16 v[16:31], v[186:189], v[220:223], v[16:31]
	v_mfma_f32_32x32x16_bf16 v[32:47], v[198:201], v[216:219], v[32:47]
	v_mfma_f32_32x32x16_bf16 v[0:15], v[198:201], v[220:223], v[0:15]
	s_waitcnt lgkmcnt(0)
	ds_read_b128 v[186:189], v134 offset:40960
	ds_read_b128 v[198:201], v134 offset:45056
	v_mfma_f32_32x32x16_bf16 v[96:111], v[212:215], v[190:193], v[96:111]
	v_mfma_f32_32x32x16_bf16 v[64:79], v[212:215], v[194:197], v[64:79]
	v_mfma_f32_32x32x16_bf16 v[112:127], v[224:227], v[190:193], v[112:127]
	v_mfma_f32_32x32x16_bf16 v[80:95], v[224:227], v[194:197], v[80:95]
	s_waitcnt vmcnt(0)
	s_barrier
; #define MFMA(a, b, c) __builtin_amdgcn_mfma_f32_32x32x16_bf16((a), (b), (c), 0, 0, 0)
;     ...
;   for (int kt = 0; kt < nk; ++kt) {
;     if (DIST == 2 && kt + 1 < nk) {
;       if (NLD == 6) asm volatile("s_waitcnt vmcnt(6)" ::: "memory");
;       else if (NLD == 5) asm volatile("s_waitcnt vmcnt(5)" ::: "memory");
;       else asm volatile("s_waitcnt vmcnt(8)" ::: "memory");
;     } else {
;       asm volatile("s_waitcnt vmcnt(0)" ::: "memory");
;     }
;     __builtin_amdgcn_s_barrier();
;     const bool pre = (kt + DIST < nk);
;     const char* base = smem + (kt % NSTG) * STAGE;
;     const char* pa = base + (wrow_act + r) * 128;
;     const char* pw = base + ABYTES + (wrow_w + r) * 128;
;     constexpr int NM = NI * MJ;
;     constexpr int PPS = (NLD + 1) / 2;
; #pragma unroll
;     for (int s = 0; s < 4; ++s) {
;       bf16x8 af[MJ], wf[NI];
; #pragma unroll
;       for (int j = 0; j < MJ; ++j) af[j] = *(const bf16x8*)(pa + j * 32 * 128 + xo[s]);
; #pragma unroll
;       for (int i = 0; i < NI; ++i) wf[i] = *(const bf16x8*)(pw + i * 32 * 128 + xo[s]);
; #pragma unroll
;       for (int m = 0; m < NM; ++m) {
;         const int i = m / MJ, j = m % MJ;
;         acc[i][j] = MFMA(wf[i], af[j], acc[i][j]);
;         if (s < 2 && NM >= PPS) {
;           constexpr int EVERY = (NM / PPS) > 0 ? (NM / PPS) : 1;
;           if ((m + 1) % EVERY == 0) {
;             const int pc = s * PPS + (m + 1) / EVERY - 1;
;             if ((m + 1) / EVERY <= PPS && pc < NLD) {
;               __builtin_amdgcn_sched_barrier(0);
;               if (pre) issue_piece(kt + DIST, pc);
;               __builtin_amdgcn_sched_barrier(0);
;             }
;           }
;         }
;         if (s < 2 && NM < PPS) {
;           const int slot = s * NM + m;
;           __builtin_amdgcn_sched_barrier(0);
; #pragma unroll
;           for (int pc = 0; pc < NLD; ++pc)
;             if ((pc * 2 * NM) / NLD == slot && pre) issue_piece(kt + DIST, pc);
;           __builtin_amdgcn_sched_barrier(0);
;         }
;       }
;     }
	s_waitcnt lgkmcnt(0)
	v_mfma_f32_32x32x16_bf16 v[48:63], v[186:189], v[190:193], v[48:63]
	v_mfma_f32_32x32x16_bf16 v[16:31], v[186:189], v[194:197], v[16:31]
	ds_read_b128 v[186:189], v138
	ds_read_b128 v[216:219], v142
	ds_read_b128 v[220:223], v142 offset:4096
	ds_read_b128 v[224:227], v138 offset:4096
	ds_read_b128 v[228:231], v138 offset:8192
	ds_read_b128 v[206:209], v138 offset:12288
	v_mfma_f32_32x32x16_bf16 v[32:47], v[198:201], v[190:193], v[32:47]
	v_mfma_f32_32x32x16_bf16 v[0:15], v[198:201], v[194:197], v[0:15]
	s_waitcnt lgkmcnt(0)
	v_mfma_f32_32x32x16_bf16 v[96:111], v[186:189], v[216:219], v[96:111]
	v_mfma_f32_32x32x16_bf16 v[64:79], v[186:189], v[220:223], v[64:79]
	v_lshl_add_u64 v[186:187], v[130:131], 0, s[0:1]
	v_readfirstlane_b32 s0, v184
	s_mov_b32 m0, s0
	s_nop 0
	global_load_lds_dwordx4 v[186:187], off
	v_mfma_f32_32x32x16_bf16 v[112:127], v[224:227], v[216:219], v[112:127]
	v_mfma_f32_32x32x16_bf16 v[80:95], v[224:227], v[220:223], v[80:95]
	s_mov_b64 s[6:7], 0x32000
	v_readfirstlane_b32 s1, v183
	v_lshl_add_u64 v[186:187], v[130:131], 0, s[6:7]
	s_mov_b32 m0, s1
	s_nop 0
	global_load_lds_dwordx4 v[186:187], off
	v_mfma_f32_32x32x16_bf16 v[48:63], v[228:231], v[216:219], v[48:63]
	v_mfma_f32_32x32x16_bf16 v[16:31], v[228:231], v[220:223], v[16:31]
	s_mov_b64 s[8:9], 0x34000
	v_readfirstlane_b32 s2, v182
	v_lshl_add_u64 v[186:187], v[130:131], 0, s[8:9]
	s_mov_b32 m0, s2
	s_nop 0
	global_load_lds_dwordx4 v[186:187], off
	v_mfma_f32_32x32x16_bf16 v[32:47], v[206:209], v[216:219], v[32:47]
	v_mfma_f32_32x32x16_bf16 v[0:15], v[206:209], v[220:223], v[0:15]
	s_mov_b64 s[10:11], 0x36000
	v_readfirstlane_b32 s3, v181
	v_lshl_add_u64 v[186:187], v[130:131], 0, s[10:11]
	s_mov_b32 m0, s3
	s_nop 0
	global_load_lds_dwordx4 v[186:187], off
	ds_read_b128 v[186:189], v144
	ds_read_b128 v[190:193], v151
	ds_read_b128 v[194:197], v151 offset:4096
	ds_read_b128 v[198:201], v144 offset:4096
	ds_read_b128 v[202:205], v144 offset:8192
	ds_read_b128 v[232:235], v144 offset:12288
	s_waitcnt lgkmcnt(0)
	ds_read_b128 v[212:215], v143
	ds_read_b128 v[216:219], v153
	ds_read_b128 v[220:223], v153 offset:4096
	ds_read_b128 v[224:227], v143 offset:4096
	v_mfma_f32_32x32x16_bf16 v[96:111], v[186:189], v[190:193], v[96:111]
	v_mfma_f32_32x32x16_bf16 v[64:79], v[186:189], v[194:197], v[64:79]
	v_readfirstlane_b32 s4, v162
	s_mov_b32 m0, s4
	s_nop 0
	global_load_lds_dwordx4 v[210:211], off
	v_mfma_f32_32x32x16_bf16 v[112:127], v[198:201], v[190:193], v[112:127]
	v_mfma_f32_32x32x16_bf16 v[80:95], v[198:201], v[194:197], v[80:95]
	v_readfirstlane_b32 s5, v165
	v_lshl_add_u64 v[186:187], v[128:129], 0, s[6:7]
	s_mov_b32 m0, s5
	s_nop 0
	global_load_lds_dwordx4 v[186:187], off
	v_mfma_f32_32x32x16_bf16 v[48:63], v[202:205], v[190:193], v[48:63]
	v_mfma_f32_32x32x16_bf16 v[16:31], v[202:205], v[194:197], v[16:31]
	v_readfirstlane_b32 s6, v164
	v_lshl_add_u64 v[186:187], v[128:129], 0, s[8:9]
	s_mov_b32 m0, s6
	s_nop 0
	global_load_lds_dwordx4 v[186:187], off
	v_mfma_f32_32x32x16_bf16 v[32:47], v[232:235], v[190:193], v[32:47]
	v_mfma_f32_32x32x16_bf16 v[0:15], v[232:235], v[194:197], v[0:15]
	v_readfirstlane_b32 s7, v163
	v_lshl_add_u64 v[186:187], v[128:129], 0, s[10:11]
	s_mov_b32 m0, s7
	s_nop 0
	global_load_lds_dwordx4 v[186:187], off
	s_mov_b64 s[8:9], 0x38000
	v_lshl_add_u64 v[210:211], v[128:129], 0, s[8:9]
	s_waitcnt lgkmcnt(0)
	ds_read_b128 v[186:189], v143 offset:8192
	ds_read_b128 v[198:201], v143 offset:12288
	v_mfma_f32_32x32x16_bf16 v[96:111], v[212:215], v[216:219], v[96:111]
	v_mfma_f32_32x32x16_bf16 v[64:79], v[212:215], v[220:223], v[64:79]
	v_mfma_f32_32x32x16_bf16 v[112:127], v[224:227], v[216:219], v[112:127]
	v_mfma_f32_32x32x16_bf16 v[80:95], v[224:227], v[220:223], v[80:95]
	s_waitcnt lgkmcnt(0)
	ds_read_b128 v[212:215], v141
	ds_read_b128 v[190:193], v152
	ds_read_b128 v[194:197], v152 offset:4096
	ds_read_b128 v[224:227], v141 offset:4096
	v_mfma_f32_32x32x16_bf16 v[48:63], v[186:189], v[216:219], v[48:63]
	v_mfma_f32_32x32x16_bf16 v[16:31], v[186:189], v[220:223], v[16:31]
	v_mfma_f32_32x32x16_bf16 v[32:47], v[198:201], v[216:219], v[32:47]
	v_mfma_f32_32x32x16_bf16 v[0:15], v[198:201], v[220:223], v[0:15]
	s_waitcnt lgkmcnt(0)
	ds_read_b128 v[186:189], v141 offset:8192
	ds_read_b128 v[198:201], v141 offset:12288
	v_mfma_f32_32x32x16_bf16 v[96:111], v[212:215], v[190:193], v[96:111]
	v_mfma_f32_32x32x16_bf16 v[64:79], v[212:215], v[194:197], v[64:79]
	v_mfma_f32_32x32x16_bf16 v[112:127], v[224:227], v[190:193], v[112:127]
	v_mfma_f32_32x32x16_bf16 v[80:95], v[224:227], v[194:197], v[80:95]
	s_waitcnt vmcnt(0)
	s_barrier
; #define MFMA(a, b, c) __builtin_amdgcn_mfma_f32_32x32x16_bf16((a), (b), (c), 0, 0, 0)
;     ...
;   for (int kt = 0; kt < nk; ++kt) {
;     if (DIST == 2 && kt + 1 < nk) {
;       if (NLD == 6) asm volatile("s_waitcnt vmcnt(6)" ::: "memory");
;       else if (NLD == 5) asm volatile("s_waitcnt vmcnt(5)" ::: "memory");
;       else asm volatile("s_waitcnt vmcnt(8)" ::: "memory");
;     } else {
;       asm volatile("s_waitcnt vmcnt(0)" ::: "memory");
;     }
;     __builtin_amdgcn_s_barrier();
;     const bool pre = (kt + DIST < nk);
;     const char* base = smem + (kt % NSTG) * STAGE;
;     const char* pa = base + (wrow_act + r) * 128;
;     const char* pw = base + ABYTES + (wrow_w + r) * 128;
;     constexpr int NM = NI * MJ;
;     constexpr int PPS = (NLD + 1) / 2;
; #pragma unroll
;     for (int s = 0; s < 4; ++s) {
;       bf16x8 af[MJ], wf[NI];
; #pragma unroll
;       for (int j = 0; j < MJ; ++j) af[j] = *(const bf16x8*)(pa + j * 32 * 128 + xo[s]);
; #pragma unroll
;       for (int i = 0; i < NI; ++i) wf[i] = *(const bf16x8*)(pw + i * 32 * 128 + xo[s]);
; #pragma unroll
;       for (int m = 0; m < NM; ++m) {
;         const int i = m / MJ, j = m % MJ;
;         acc[i][j] = MFMA(wf[i], af[j], acc[i][j]);
;         if (s < 2 && NM >= PPS) {
;           constexpr int EVERY = (NM / PPS) > 0 ? (NM / PPS) : 1;
;           if ((m + 1) % EVERY == 0) {
;             const int pc = s * PPS + (m + 1) / EVERY - 1;
;             if ((m + 1) / EVERY <= PPS && pc < NLD) {
;               __builtin_amdgcn_sched_barrier(0);
;               if (pre) issue_piece(kt + DIST, pc);
;               __builtin_amdgcn_sched_barrier(0);
;             }
;           }
;         }
;         if (s < 2 && NM < PPS) {
;           const int slot = s * NM + m;
;           __builtin_amdgcn_sched_barrier(0);
; #pragma unroll
;           for (int pc = 0; pc < NLD; ++pc)
;             if ((pc * 2 * NM) / NLD == slot && pre) issue_piece(kt + DIST, pc);
;           __builtin_amdgcn_sched_barrier(0);
;         }
;       }
;     }
	s_waitcnt lgkmcnt(0)
	v_mfma_f32_32x32x16_bf16 v[48:63], v[186:189], v[190:193], v[48:63]
	v_mfma_f32_32x32x16_bf16 v[16:31], v[186:189], v[194:197], v[16:31]
	ds_read_b128 v[186:189], v132 offset:32768
	ds_read_b128 v[216:219], v136
	ds_read_b128 v[220:223], v136 offset:4096
	ds_read_b128 v[224:227], v132 offset:36864
	ds_read_b128 v[228:231], v132 offset:40960
	ds_read_b128 v[206:209], v132 offset:45056
	v_mfma_f32_32x32x16_bf16 v[32:47], v[198:201], v[190:193], v[32:47]
	v_mfma_f32_32x32x16_bf16 v[0:15], v[198:201], v[194:197], v[0:15]
	s_waitcnt lgkmcnt(0)
	v_mfma_f32_32x32x16_bf16 v[96:111], v[186:189], v[216:219], v[96:111]
	v_mfma_f32_32x32x16_bf16 v[64:79], v[186:189], v[220:223], v[64:79]
	v_lshl_add_u64 v[186:187], v[130:131], 0, s[8:9]
	v_readfirstlane_b32 s8, v155
	s_mov_b32 m0, s8
	s_nop 0
	global_load_lds_dwordx4 v[186:187], off
	v_mfma_f32_32x32x16_bf16 v[112:127], v[224:227], v[216:219], v[112:127]
	v_mfma_f32_32x32x16_bf16 v[80:95], v[224:227], v[220:223], v[80:95]
	s_mov_b64 s[14:15], 0x3a000
	v_readfirstlane_b32 s9, v158
	v_lshl_add_u64 v[186:187], v[130:131], 0, s[14:15]
	s_mov_b32 m0, s9
	s_nop 0
	global_load_lds_dwordx4 v[186:187], off
	v_mfma_f32_32x32x16_bf16 v[48:63], v[228:231], v[216:219], v[48:63]
	v_mfma_f32_32x32x16_bf16 v[16:31], v[228:231], v[220:223], v[16:31]
	s_mov_b64 s[16:17], 0x3c000
	v_readfirstlane_b32 s10, v157
	v_lshl_add_u64 v[186:187], v[130:131], 0, s[16:17]
	s_mov_b32 m0, s10
	s_nop 0
	global_load_lds_dwordx4 v[186:187], off
	v_mfma_f32_32x32x16_bf16 v[32:47], v[206:209], v[216:219], v[32:47]
	v_mfma_f32_32x32x16_bf16 v[0:15], v[206:209], v[220:223], v[0:15]
	s_mov_b64 s[18:19], 0x3e000
	v_readfirstlane_b32 s11, v156
	v_lshl_add_u64 v[186:187], v[130:131], 0, s[18:19]
	s_mov_b32 m0, s11
	s_nop 0
	global_load_lds_dwordx4 v[186:187], off
	ds_read_b128 v[186:189], v133 offset:32768
	ds_read_b128 v[190:193], v137
	ds_read_b128 v[194:197], v137 offset:4096
	ds_read_b128 v[198:201], v133 offset:36864
	ds_read_b128 v[202:205], v133 offset:40960
	ds_read_b128 v[232:235], v133 offset:45056
	s_waitcnt lgkmcnt(0)
	ds_read_b128 v[212:215], v135 offset:32768
	ds_read_b128 v[216:219], v140
	ds_read_b128 v[220:223], v140 offset:4096
	ds_read_b128 v[224:227], v135 offset:36864
	v_mfma_f32_32x32x16_bf16 v[96:111], v[186:189], v[190:193], v[96:111]
	v_mfma_f32_32x32x16_bf16 v[64:79], v[186:189], v[194:197], v[64:79]
	v_readfirstlane_b32 s12, v154
	s_mov_b32 m0, s12
	s_nop 0
	global_load_lds_dwordx4 v[210:211], off
	v_mfma_f32_32x32x16_bf16 v[112:127], v[198:201], v[190:193], v[112:127]
	v_mfma_f32_32x32x16_bf16 v[80:95], v[198:201], v[194:197], v[80:95]
	v_readfirstlane_b32 s13, v159
	v_lshl_add_u64 v[186:187], v[128:129], 0, s[14:15]
	s_mov_b32 m0, s13
	s_nop 0
	global_load_lds_dwordx4 v[186:187], off
	v_mfma_f32_32x32x16_bf16 v[48:63], v[202:205], v[190:193], v[48:63]
	v_mfma_f32_32x32x16_bf16 v[16:31], v[202:205], v[194:197], v[16:31]
	v_readfirstlane_b32 s14, v160
	v_lshl_add_u64 v[186:187], v[128:129], 0, s[16:17]
	s_mov_b32 m0, s14
	s_nop 0
	global_load_lds_dwordx4 v[186:187], off
	v_mfma_f32_32x32x16_bf16 v[32:47], v[232:235], v[190:193], v[32:47]
	v_mfma_f32_32x32x16_bf16 v[0:15], v[232:235], v[194:197], v[0:15]
	v_readfirstlane_b32 s15, v161
	v_lshl_add_u64 v[186:187], v[128:129], 0, s[18:19]
	s_mov_b32 m0, s15
	s_nop 0
	global_load_lds_dwordx4 v[186:187], off
	s_mov_b64 s[16:17], 0x40000
	v_lshl_add_u64 v[210:211], v[128:129], 0, s[16:17]
	s_waitcnt lgkmcnt(0)
	ds_read_b128 v[186:189], v135 offset:40960
	ds_read_b128 v[198:201], v135 offset:45056
	v_mfma_f32_32x32x16_bf16 v[96:111], v[212:215], v[216:219], v[96:111]
	v_mfma_f32_32x32x16_bf16 v[64:79], v[212:215], v[220:223], v[64:79]
	v_mfma_f32_32x32x16_bf16 v[112:127], v[224:227], v[216:219], v[112:127]
	v_mfma_f32_32x32x16_bf16 v[80:95], v[224:227], v[220:223], v[80:95]
	s_waitcnt lgkmcnt(0)
	ds_read_b128 v[212:215], v134 offset:32768
	ds_read_b128 v[190:193], v139
	ds_read_b128 v[194:197], v139 offset:4096
	ds_read_b128 v[224:227], v134 offset:36864
	v_mfma_f32_32x32x16_bf16 v[48:63], v[186:189], v[216:219], v[48:63]
	v_mfma_f32_32x32x16_bf16 v[16:31], v[186:189], v[220:223], v[16:31]
	v_mfma_f32_32x32x16_bf16 v[32:47], v[198:201], v[216:219], v[32:47]
	v_mfma_f32_32x32x16_bf16 v[0:15], v[198:201], v[220:223], v[0:15]
	s_waitcnt lgkmcnt(0)
	ds_read_b128 v[186:189], v134 offset:40960
	ds_read_b128 v[198:201], v134 offset:45056
	v_mfma_f32_32x32x16_bf16 v[96:111], v[212:215], v[190:193], v[96:111]
	v_mfma_f32_32x32x16_bf16 v[64:79], v[212:215], v[194:197], v[64:79]
	v_mfma_f32_32x32x16_bf16 v[112:127], v[224:227], v[190:193], v[112:127]
	v_mfma_f32_32x32x16_bf16 v[80:95], v[224:227], v[194:197], v[80:95]
	s_waitcnt vmcnt(0)
	s_barrier
; #define MFMA(a, b, c) __builtin_amdgcn_mfma_f32_32x32x16_bf16((a), (b), (c), 0, 0, 0)
;     ...
;   for (int kt = 0; kt < nk; ++kt) {
;     if (DIST == 2 && kt + 1 < nk) {
;       if (NLD == 6) asm volatile("s_waitcnt vmcnt(6)" ::: "memory");
;       else if (NLD == 5) asm volatile("s_waitcnt vmcnt(5)" ::: "memory");
;       else asm volatile("s_waitcnt vmcnt(8)" ::: "memory");
;     } else {
;       asm volatile("s_waitcnt vmcnt(0)" ::: "memory");
;     }
;     __builtin_amdgcn_s_barrier();
;     const bool pre = (kt + DIST < nk);
;     const char* base = smem + (kt % NSTG) * STAGE;
;     const char* pa = base + (wrow_act + r) * 128;
;     const char* pw = base + ABYTES + (wrow_w + r) * 128;
;     constexpr int NM = NI * MJ;
;     constexpr int PPS = (NLD + 1) / 2;
; #pragma unroll
;     for (int s = 0; s < 4; ++s) {
;       bf16x8 af[MJ], wf[NI];
; #pragma unroll
;       for (int j = 0; j < MJ; ++j) af[j] = *(const bf16x8*)(pa + j * 32 * 128 + xo[s]);
; #pragma unroll
;       for (int i = 0; i < NI; ++i) wf[i] = *(const bf16x8*)(pw + i * 32 * 128 + xo[s]);
; #pragma unroll
;       for (int m = 0; m < NM; ++m) {
;         const int i = m / MJ, j = m % MJ;
;         acc[i][j] = MFMA(wf[i], af[j], acc[i][j]);
;         if (s < 2 && NM >= PPS) {
;           constexpr int EVERY = (NM / PPS) > 0 ? (NM / PPS) : 1;
;           if ((m + 1) % EVERY == 0) {
;             const int pc = s * PPS + (m + 1) / EVERY - 1;
;             if ((m + 1) / EVERY <= PPS && pc < NLD) {
;               __builtin_amdgcn_sched_barrier(0);
;               if (pre) issue_piece(kt + DIST, pc);
;               __builtin_amdgcn_sched_barrier(0);
;             }
;           }
;         }
;         if (s < 2 && NM < PPS) {
;           const int slot = s * NM + m;
;           __builtin_amdgcn_sched_barrier(0);
; #pragma unroll
;           for (int pc = 0; pc < NLD; ++pc)
;             if ((pc * 2 * NM) / NLD == slot && pre) issue_piece(kt + DIST, pc);
;           __builtin_amdgcn_sched_barrier(0);
;         }
;       }
;     }
	s_waitcnt lgkmcnt(0)
	v_mfma_f32_32x32x16_bf16 v[48:63], v[186:189], v[190:193], v[48:63]
	v_mfma_f32_32x32x16_bf16 v[16:31], v[186:189], v[194:197], v[16:31]
	ds_read_b128 v[186:189], v138
	ds_read_b128 v[216:219], v142
	ds_read_b128 v[220:223], v142 offset:4096
	ds_read_b128 v[224:227], v138 offset:4096
	ds_read_b128 v[228:231], v138 offset:8192
	ds_read_b128 v[206:209], v138 offset:12288
	v_mfma_f32_32x32x16_bf16 v[32:47], v[198:201], v[190:193], v[32:47]
	v_mfma_f32_32x32x16_bf16 v[0:15], v[198:201], v[194:197], v[0:15]
	s_waitcnt lgkmcnt(0)
	v_mfma_f32_32x32x16_bf16 v[96:111], v[186:189], v[216:219], v[96:111]
	v_mfma_f32_32x32x16_bf16 v[64:79], v[186:189], v[220:223], v[64:79]
	v_lshl_add_u64 v[186:187], v[130:131], 0, s[16:17]
	s_mov_b32 m0, s0
	s_nop 0
	global_load_lds_dwordx4 v[186:187], off
	v_mfma_f32_32x32x16_bf16 v[112:127], v[224:227], v[216:219], v[112:127]
	v_mfma_f32_32x32x16_bf16 v[80:95], v[224:227], v[220:223], v[80:95]
	s_mov_b64 s[16:17], 0x42000
	v_lshl_add_u64 v[186:187], v[130:131], 0, s[16:17]
	s_mov_b32 m0, s1
	s_nop 0
	global_load_lds_dwordx4 v[186:187], off
	v_mfma_f32_32x32x16_bf16 v[48:63], v[228:231], v[216:219], v[48:63]
	v_mfma_f32_32x32x16_bf16 v[16:31], v[228:231], v[220:223], v[16:31]
	s_mov_b64 s[18:19], 0x44000
	v_lshl_add_u64 v[186:187], v[130:131], 0, s[18:19]
	s_mov_b32 m0, s2
	s_nop 0
	global_load_lds_dwordx4 v[186:187], off
	v_mfma_f32_32x32x16_bf16 v[32:47], v[206:209], v[216:219], v[32:47]
	v_mfma_f32_32x32x16_bf16 v[0:15], v[206:209], v[220:223], v[0:15]
	s_mov_b64 s[20:21], 0x46000
	v_lshl_add_u64 v[186:187], v[130:131], 0, s[20:21]
	s_mov_b32 m0, s3
	s_nop 0
	global_load_lds_dwordx4 v[186:187], off
	ds_read_b128 v[186:189], v144
	ds_read_b128 v[190:193], v151
	ds_read_b128 v[194:197], v151 offset:4096
	ds_read_b128 v[198:201], v144 offset:4096
	ds_read_b128 v[202:205], v144 offset:8192
	ds_read_b128 v[232:235], v144 offset:12288
	s_waitcnt lgkmcnt(0)
	ds_read_b128 v[212:215], v143
	ds_read_b128 v[216:219], v153
	ds_read_b128 v[220:223], v153 offset:4096
	ds_read_b128 v[224:227], v143 offset:4096
	v_mfma_f32_32x32x16_bf16 v[96:111], v[186:189], v[190:193], v[96:111]
	v_mfma_f32_32x32x16_bf16 v[64:79], v[186:189], v[194:197], v[64:79]
	s_mov_b32 m0, s4
	s_nop 0
	global_load_lds_dwordx4 v[210:211], off
	v_mfma_f32_32x32x16_bf16 v[112:127], v[198:201], v[190:193], v[112:127]
	v_mfma_f32_32x32x16_bf16 v[80:95], v[198:201], v[194:197], v[80:95]
	v_lshl_add_u64 v[186:187], v[128:129], 0, s[16:17]
	s_mov_b32 m0, s5
	s_nop 0
	global_load_lds_dwordx4 v[186:187], off
	v_mfma_f32_32x32x16_bf16 v[48:63], v[202:205], v[190:193], v[48:63]
	v_mfma_f32_32x32x16_bf16 v[16:31], v[202:205], v[194:197], v[16:31]
	v_lshl_add_u64 v[186:187], v[128:129], 0, s[18:19]
	s_mov_b32 m0, s6
	s_nop 0
	global_load_lds_dwordx4 v[186:187], off
	v_mfma_f32_32x32x16_bf16 v[32:47], v[232:235], v[190:193], v[32:47]
	v_mfma_f32_32x32x16_bf16 v[0:15], v[232:235], v[194:197], v[0:15]
	v_lshl_add_u64 v[186:187], v[128:129], 0, s[20:21]
	s_mov_b32 m0, s7
	s_nop 0
	global_load_lds_dwordx4 v[186:187], off
	s_mov_b64 s[16:17], 0x48000
	v_lshl_add_u64 v[210:211], v[128:129], 0, s[16:17]
	s_waitcnt lgkmcnt(0)
	ds_read_b128 v[186:189], v143 offset:8192
	ds_read_b128 v[198:201], v143 offset:12288
	v_mfma_f32_32x32x16_bf16 v[96:111], v[212:215], v[216:219], v[96:111]
	v_mfma_f32_32x32x16_bf16 v[64:79], v[212:215], v[220:223], v[64:79]
	v_mfma_f32_32x32x16_bf16 v[112:127], v[224:227], v[216:219], v[112:127]
	v_mfma_f32_32x32x16_bf16 v[80:95], v[224:227], v[220:223], v[80:95]
	s_waitcnt lgkmcnt(0)
	ds_read_b128 v[212:215], v141
	ds_read_b128 v[190:193], v152
	ds_read_b128 v[194:197], v152 offset:4096
	ds_read_b128 v[224:227], v141 offset:4096
	v_mfma_f32_32x32x16_bf16 v[48:63], v[186:189], v[216:219], v[48:63]
	v_mfma_f32_32x32x16_bf16 v[16:31], v[186:189], v[220:223], v[16:31]
	v_mfma_f32_32x32x16_bf16 v[32:47], v[198:201], v[216:219], v[32:47]
	v_mfma_f32_32x32x16_bf16 v[0:15], v[198:201], v[220:223], v[0:15]
	s_waitcnt lgkmcnt(0)
	ds_read_b128 v[186:189], v141 offset:8192
	ds_read_b128 v[198:201], v141 offset:12288
	v_mfma_f32_32x32x16_bf16 v[96:111], v[212:215], v[190:193], v[96:111]
	v_mfma_f32_32x32x16_bf16 v[64:79], v[212:215], v[194:197], v[64:79]
	v_mfma_f32_32x32x16_bf16 v[112:127], v[224:227], v[190:193], v[112:127]
	v_mfma_f32_32x32x16_bf16 v[80:95], v[224:227], v[194:197], v[80:95]
	s_waitcnt vmcnt(0)
	s_barrier
; #define MFMA(a, b, c) __builtin_amdgcn_mfma_f32_32x32x16_bf16((a), (b), (c), 0, 0, 0)
;     ...
;   for (int kt = 0; kt < nk; ++kt) {
;     if (DIST == 2 && kt + 1 < nk) {
;       if (NLD == 6) asm volatile("s_waitcnt vmcnt(6)" ::: "memory");
;       else if (NLD == 5) asm volatile("s_waitcnt vmcnt(5)" ::: "memory");
;       else asm volatile("s_waitcnt vmcnt(8)" ::: "memory");
;     } else {
;       asm volatile("s_waitcnt vmcnt(0)" ::: "memory");
;     }
;     __builtin_amdgcn_s_barrier();
;     const bool pre = (kt + DIST < nk);
;     const char* base = smem + (kt % NSTG) * STAGE;
;     const char* pa = base + (wrow_act + r) * 128;
;     const char* pw = base + ABYTES + (wrow_w + r) * 128;
;     constexpr int NM = NI * MJ;
;     constexpr int PPS = (NLD + 1) / 2;
; #pragma unroll
;     for (int s = 0; s < 4; ++s) {
;       bf16x8 af[MJ], wf[NI];
; #pragma unroll
;       for (int j = 0; j < MJ; ++j) af[j] = *(const bf16x8*)(pa + j * 32 * 128 + xo[s]);
; #pragma unroll
;       for (int i = 0; i < NI; ++i) wf[i] = *(const bf16x8*)(pw + i * 32 * 128 + xo[s]);
; #pragma unroll
;       for (int m = 0; m < NM; ++m) {
;         const int i = m / MJ, j = m % MJ;
;         acc[i][j] = MFMA(wf[i], af[j], acc[i][j]);
;         if (s < 2 && NM >= PPS) {
;           constexpr int EVERY = (NM / PPS) > 0 ? (NM / PPS) : 1;
;           if ((m + 1) % EVERY == 0) {
;             const int pc = s * PPS + (m + 1) / EVERY - 1;
;             if ((m + 1) / EVERY <= PPS && pc < NLD) {
;               __builtin_amdgcn_sched_barrier(0);
;               if (pre) issue_piece(kt + DIST, pc);
;               __builtin_amdgcn_sched_barrier(0);
;             }
;           }
;         }
;         if (s < 2 && NM < PPS) {
;           const int slot = s * NM + m;
;           __builtin_amdgcn_sched_barrier(0);
; #pragma unroll
;           for (int pc = 0; pc < NLD; ++pc)
;             if ((pc * 2 * NM) / NLD == slot && pre) issue_piece(kt + DIST, pc);
;           __builtin_amdgcn_sched_barrier(0);
;         }
;       }
;     }
	s_waitcnt lgkmcnt(0)
	v_mfma_f32_32x32x16_bf16 v[48:63], v[186:189], v[190:193], v[48:63]
	v_mfma_f32_32x32x16_bf16 v[16:31], v[186:189], v[194:197], v[16:31]
	ds_read_b128 v[186:189], v132 offset:32768
	ds_read_b128 v[216:219], v136
	ds_read_b128 v[220:223], v136 offset:4096
	ds_read_b128 v[224:227], v132 offset:36864
	ds_read_b128 v[228:231], v132 offset:40960
	ds_read_b128 v[206:209], v132 offset:45056
	v_mfma_f32_32x32x16_bf16 v[32:47], v[198:201], v[190:193], v[32:47]
	v_mfma_f32_32x32x16_bf16 v[0:15], v[198:201], v[194:197], v[0:15]
	s_waitcnt lgkmcnt(0)
	v_mfma_f32_32x32x16_bf16 v[96:111], v[186:189], v[216:219], v[96:111]
	v_mfma_f32_32x32x16_bf16 v[64:79], v[186:189], v[220:223], v[64:79]
	v_lshl_add_u64 v[186:187], v[130:131], 0, s[16:17]
	s_mov_b32 m0, s8
	s_nop 0
	global_load_lds_dwordx4 v[186:187], off
	v_mfma_f32_32x32x16_bf16 v[112:127], v[224:227], v[216:219], v[112:127]
	v_mfma_f32_32x32x16_bf16 v[80:95], v[224:227], v[220:223], v[80:95]
	s_mov_b64 s[16:17], 0x4a000
	v_lshl_add_u64 v[186:187], v[130:131], 0, s[16:17]
	s_mov_b32 m0, s9
	s_nop 0
	global_load_lds_dwordx4 v[186:187], off
	v_mfma_f32_32x32x16_bf16 v[48:63], v[228:231], v[216:219], v[48:63]
	v_mfma_f32_32x32x16_bf16 v[16:31], v[228:231], v[220:223], v[16:31]
	s_mov_b64 s[18:19], 0x4c000
	v_lshl_add_u64 v[186:187], v[130:131], 0, s[18:19]
	s_mov_b32 m0, s10
	s_nop 0
	global_load_lds_dwordx4 v[186:187], off
	v_mfma_f32_32x32x16_bf16 v[32:47], v[206:209], v[216:219], v[32:47]
	v_mfma_f32_32x32x16_bf16 v[0:15], v[206:209], v[220:223], v[0:15]
	s_mov_b64 s[20:21], 0x4e000
	v_lshl_add_u64 v[186:187], v[130:131], 0, s[20:21]
	s_mov_b32 m0, s11
	s_nop 0
	global_load_lds_dwordx4 v[186:187], off
	ds_read_b128 v[186:189], v133 offset:32768
	ds_read_b128 v[190:193], v137
	ds_read_b128 v[194:197], v137 offset:4096
	ds_read_b128 v[198:201], v133 offset:36864
	ds_read_b128 v[202:205], v133 offset:40960
	ds_read_b128 v[232:235], v133 offset:45056
	s_waitcnt lgkmcnt(0)
	ds_read_b128 v[212:215], v135 offset:32768
	ds_read_b128 v[216:219], v140
	ds_read_b128 v[220:223], v140 offset:4096
	ds_read_b128 v[224:227], v135 offset:36864
	v_mfma_f32_32x32x16_bf16 v[96:111], v[186:189], v[190:193], v[96:111]
	v_mfma_f32_32x32x16_bf16 v[64:79], v[186:189], v[194:197], v[64:79]
	s_mov_b32 m0, s12
	s_nop 0
	global_load_lds_dwordx4 v[210:211], off
	v_mfma_f32_32x32x16_bf16 v[112:127], v[198:201], v[190:193], v[112:127]
	v_mfma_f32_32x32x16_bf16 v[80:95], v[198:201], v[194:197], v[80:95]
	v_lshl_add_u64 v[186:187], v[128:129], 0, s[16:17]
	s_mov_b32 m0, s13
	s_nop 0
	global_load_lds_dwordx4 v[186:187], off
	v_mfma_f32_32x32x16_bf16 v[48:63], v[202:205], v[190:193], v[48:63]
	v_mfma_f32_32x32x16_bf16 v[16:31], v[202:205], v[194:197], v[16:31]
	v_lshl_add_u64 v[186:187], v[128:129], 0, s[18:19]
	s_mov_b32 m0, s14
	s_nop 0
	global_load_lds_dwordx4 v[186:187], off
	v_mfma_f32_32x32x16_bf16 v[32:47], v[232:235], v[190:193], v[32:47]
	v_mfma_f32_32x32x16_bf16 v[0:15], v[232:235], v[194:197], v[0:15]
	v_lshl_add_u64 v[186:187], v[128:129], 0, s[20:21]
	s_mov_b32 m0, s15
	s_nop 0
	global_load_lds_dwordx4 v[186:187], off
	s_mov_b64 s[16:17], 0x50000
	v_lshl_add_u64 v[210:211], v[128:129], 0, s[16:17]
	s_waitcnt lgkmcnt(0)
	ds_read_b128 v[186:189], v135 offset:40960
	ds_read_b128 v[198:201], v135 offset:45056
	v_mfma_f32_32x32x16_bf16 v[96:111], v[212:215], v[216:219], v[96:111]
	v_mfma_f32_32x32x16_bf16 v[64:79], v[212:215], v[220:223], v[64:79]
	v_mfma_f32_32x32x16_bf16 v[112:127], v[224:227], v[216:219], v[112:127]
	v_mfma_f32_32x32x16_bf16 v[80:95], v[224:227], v[220:223], v[80:95]
	s_waitcnt lgkmcnt(0)
	ds_read_b128 v[212:215], v134 offset:32768
	ds_read_b128 v[190:193], v139
	ds_read_b128 v[194:197], v139 offset:4096
	ds_read_b128 v[224:227], v134 offset:36864
	v_mfma_f32_32x32x16_bf16 v[48:63], v[186:189], v[216:219], v[48:63]
	v_mfma_f32_32x32x16_bf16 v[16:31], v[186:189], v[220:223], v[16:31]
	v_mfma_f32_32x32x16_bf16 v[32:47], v[198:201], v[216:219], v[32:47]
	v_mfma_f32_32x32x16_bf16 v[0:15], v[198:201], v[220:223], v[0:15]
	s_waitcnt lgkmcnt(0)
	ds_read_b128 v[186:189], v134 offset:40960
	ds_read_b128 v[198:201], v134 offset:45056
	v_mfma_f32_32x32x16_bf16 v[96:111], v[212:215], v[190:193], v[96:111]
	v_mfma_f32_32x32x16_bf16 v[64:79], v[212:215], v[194:197], v[64:79]
	v_mfma_f32_32x32x16_bf16 v[112:127], v[224:227], v[190:193], v[112:127]
	v_mfma_f32_32x32x16_bf16 v[80:95], v[224:227], v[194:197], v[80:95]
	s_waitcnt vmcnt(0)
	s_barrier
; #define MFMA(a, b, c) __builtin_amdgcn_mfma_f32_32x32x16_bf16((a), (b), (c), 0, 0, 0)
;     ...
;   for (int kt = 0; kt < nk; ++kt) {
;     if (DIST == 2 && kt + 1 < nk) {
;       if (NLD == 6) asm volatile("s_waitcnt vmcnt(6)" ::: "memory");
;       else if (NLD == 5) asm volatile("s_waitcnt vmcnt(5)" ::: "memory");
;       else asm volatile("s_waitcnt vmcnt(8)" ::: "memory");
;     } else {
;       asm volatile("s_waitcnt vmcnt(0)" ::: "memory");
;     }
;     __builtin_amdgcn_s_barrier();
;     const bool pre = (kt + DIST < nk);
;     const char* base = smem + (kt % NSTG) * STAGE;
;     const char* pa = base + (wrow_act + r) * 128;
;     const char* pw = base + ABYTES + (wrow_w + r) * 128;
;     constexpr int NM = NI * MJ;
;     constexpr int PPS = (NLD + 1) / 2;
; #pragma unroll
;     for (int s = 0; s < 4; ++s) {
;       bf16x8 af[MJ], wf[NI];
; #pragma unroll
;       for (int j = 0; j < MJ; ++j) af[j] = *(const bf16x8*)(pa + j * 32 * 128 + xo[s]);
; #pragma unroll
;       for (int i = 0; i < NI; ++i) wf[i] = *(const bf16x8*)(pw + i * 32 * 128 + xo[s]);
; #pragma unroll
;       for (int m = 0; m < NM; ++m) {
;         const int i = m / MJ, j = m % MJ;
;         acc[i][j] = MFMA(wf[i], af[j], acc[i][j]);
;         if (s < 2 && NM >= PPS) {
;           constexpr int EVERY = (NM / PPS) > 0 ? (NM / PPS) : 1;
;           if ((m + 1) % EVERY == 0) {
;             const int pc = s * PPS + (m + 1) / EVERY - 1;
;             if ((m + 1) / EVERY <= PPS && pc < NLD) {
;               __builtin_amdgcn_sched_barrier(0);
;               if (pre) issue_piece(kt + DIST, pc);
;               __builtin_amdgcn_sched_barrier(0);
;             }
;           }
;         }
;         if (s < 2 && NM < PPS) {
;           const int slot = s * NM + m;
;           __builtin_amdgcn_sched_barrier(0);
; #pragma unroll
;           for (int pc = 0; pc < NLD; ++pc)
;             if ((pc * 2 * NM) / NLD == slot && pre) issue_piece(kt + DIST, pc);
;           __builtin_amdgcn_sched_barrier(0);
;         }
;       }
;     }
	s_waitcnt lgkmcnt(0)
	v_mfma_f32_32x32x16_bf16 v[48:63], v[186:189], v[190:193], v[48:63]
	v_mfma_f32_32x32x16_bf16 v[16:31], v[186:189], v[194:197], v[16:31]
	ds_read_b128 v[186:189], v138
	ds_read_b128 v[216:219], v142
	ds_read_b128 v[220:223], v142 offset:4096
	ds_read_b128 v[224:227], v138 offset:4096
	ds_read_b128 v[228:231], v138 offset:8192
	ds_read_b128 v[206:209], v138 offset:12288
	v_mfma_f32_32x32x16_bf16 v[32:47], v[198:201], v[190:193], v[32:47]
	v_mfma_f32_32x32x16_bf16 v[0:15], v[198:201], v[194:197], v[0:15]
	s_waitcnt lgkmcnt(0)
	v_mfma_f32_32x32x16_bf16 v[96:111], v[186:189], v[216:219], v[96:111]
	v_mfma_f32_32x32x16_bf16 v[64:79], v[186:189], v[220:223], v[64:79]
	v_lshl_add_u64 v[186:187], v[130:131], 0, s[16:17]
	s_mov_b32 m0, s0
	s_nop 0
	global_load_lds_dwordx4 v[186:187], off
	v_mfma_f32_32x32x16_bf16 v[112:127], v[224:227], v[216:219], v[112:127]
	v_mfma_f32_32x32x16_bf16 v[80:95], v[224:227], v[220:223], v[80:95]
	s_mov_b64 s[16:17], 0x52000
	v_lshl_add_u64 v[186:187], v[130:131], 0, s[16:17]
	s_mov_b32 m0, s1
	s_nop 0
	global_load_lds_dwordx4 v[186:187], off
	v_mfma_f32_32x32x16_bf16 v[48:63], v[228:231], v[216:219], v[48:63]
	v_mfma_f32_32x32x16_bf16 v[16:31], v[228:231], v[220:223], v[16:31]
	s_mov_b64 s[0:1], 0x54000
	v_lshl_add_u64 v[186:187], v[130:131], 0, s[0:1]
	s_mov_b32 m0, s2
	s_nop 0
	global_load_lds_dwordx4 v[186:187], off
	v_mfma_f32_32x32x16_bf16 v[32:47], v[206:209], v[216:219], v[32:47]
	v_mfma_f32_32x32x16_bf16 v[0:15], v[206:209], v[220:223], v[0:15]
	s_mov_b64 s[18:19], 0x56000
	v_lshl_add_u64 v[186:187], v[130:131], 0, s[18:19]
	s_mov_b32 m0, s3
	s_nop 0
	global_load_lds_dwordx4 v[186:187], off
	ds_read_b128 v[186:189], v144
	ds_read_b128 v[190:193], v151
	ds_read_b128 v[194:197], v151 offset:4096
	ds_read_b128 v[198:201], v144 offset:4096
	ds_read_b128 v[202:205], v144 offset:8192
	ds_read_b128 v[232:235], v144 offset:12288
	s_waitcnt lgkmcnt(0)
	ds_read_b128 v[212:215], v143
	ds_read_b128 v[216:219], v153
	ds_read_b128 v[220:223], v153 offset:4096
	ds_read_b128 v[224:227], v143 offset:4096
	v_mfma_f32_32x32x16_bf16 v[96:111], v[186:189], v[190:193], v[96:111]
	v_mfma_f32_32x32x16_bf16 v[64:79], v[186:189], v[194:197], v[64:79]
	s_mov_b32 m0, s4
	s_nop 0
	global_load_lds_dwordx4 v[210:211], off
	v_mfma_f32_32x32x16_bf16 v[112:127], v[198:201], v[190:193], v[112:127]
	v_mfma_f32_32x32x16_bf16 v[80:95], v[198:201], v[194:197], v[80:95]
	v_lshl_add_u64 v[186:187], v[128:129], 0, s[16:17]
	s_mov_b32 m0, s5
	s_nop 0
	global_load_lds_dwordx4 v[186:187], off
	v_mfma_f32_32x32x16_bf16 v[48:63], v[202:205], v[190:193], v[48:63]
	v_mfma_f32_32x32x16_bf16 v[16:31], v[202:205], v[194:197], v[16:31]
	v_lshl_add_u64 v[186:187], v[128:129], 0, s[0:1]
	s_mov_b32 m0, s6
	s_nop 0
	global_load_lds_dwordx4 v[186:187], off
	v_mfma_f32_32x32x16_bf16 v[32:47], v[232:235], v[190:193], v[32:47]
	v_mfma_f32_32x32x16_bf16 v[0:15], v[232:235], v[194:197], v[0:15]
	v_lshl_add_u64 v[186:187], v[128:129], 0, s[18:19]
	s_mov_b32 m0, s7
	s_nop 0
	global_load_lds_dwordx4 v[186:187], off
	s_mov_b64 s[0:1], 0x58000
	v_lshl_add_u64 v[210:211], v[128:129], 0, s[0:1]
	s_waitcnt lgkmcnt(0)
	ds_read_b128 v[186:189], v143 offset:8192
	ds_read_b128 v[198:201], v143 offset:12288
	v_mfma_f32_32x32x16_bf16 v[96:111], v[212:215], v[216:219], v[96:111]
	v_mfma_f32_32x32x16_bf16 v[64:79], v[212:215], v[220:223], v[64:79]
	v_mfma_f32_32x32x16_bf16 v[112:127], v[224:227], v[216:219], v[112:127]
	v_mfma_f32_32x32x16_bf16 v[80:95], v[224:227], v[220:223], v[80:95]
	s_waitcnt lgkmcnt(0)
	ds_read_b128 v[212:215], v141
	ds_read_b128 v[190:193], v152
	ds_read_b128 v[194:197], v152 offset:4096
	ds_read_b128 v[224:227], v141 offset:4096
	v_mfma_f32_32x32x16_bf16 v[48:63], v[186:189], v[216:219], v[48:63]
	v_mfma_f32_32x32x16_bf16 v[16:31], v[186:189], v[220:223], v[16:31]
	v_mfma_f32_32x32x16_bf16 v[32:47], v[198:201], v[216:219], v[32:47]
	v_mfma_f32_32x32x16_bf16 v[0:15], v[198:201], v[220:223], v[0:15]
	s_waitcnt lgkmcnt(0)
	ds_read_b128 v[186:189], v141 offset:8192
	ds_read_b128 v[198:201], v141 offset:12288
	v_mfma_f32_32x32x16_bf16 v[96:111], v[212:215], v[190:193], v[96:111]
	v_mfma_f32_32x32x16_bf16 v[64:79], v[212:215], v[194:197], v[64:79]
	v_mfma_f32_32x32x16_bf16 v[112:127], v[224:227], v[190:193], v[112:127]
	v_mfma_f32_32x32x16_bf16 v[80:95], v[224:227], v[194:197], v[80:95]
	s_waitcnt vmcnt(0)
	s_barrier
; #define MFMA(a, b, c) __builtin_amdgcn_mfma_f32_32x32x16_bf16((a), (b), (c), 0, 0, 0)
;     ...
;   for (int kt = 0; kt < nk; ++kt) {
;     if (DIST == 2 && kt + 1 < nk) {
;       if (NLD == 6) asm volatile("s_waitcnt vmcnt(6)" ::: "memory");
;       else if (NLD == 5) asm volatile("s_waitcnt vmcnt(5)" ::: "memory");
;       else asm volatile("s_waitcnt vmcnt(8)" ::: "memory");
;     } else {
;       asm volatile("s_waitcnt vmcnt(0)" ::: "memory");
;     }
;     __builtin_amdgcn_s_barrier();
;     const bool pre = (kt + DIST < nk);
;     const char* base = smem + (kt % NSTG) * STAGE;
;     const char* pa = base + (wrow_act + r) * 128;
;     const char* pw = base + ABYTES + (wrow_w + r) * 128;
;     constexpr int NM = NI * MJ;
;     constexpr int PPS = (NLD + 1) / 2;
; #pragma unroll
;     for (int s = 0; s < 4; ++s) {
;       bf16x8 af[MJ], wf[NI];
; #pragma unroll
;       for (int j = 0; j < MJ; ++j) af[j] = *(const bf16x8*)(pa + j * 32 * 128 + xo[s]);
; #pragma unroll
;       for (int i = 0; i < NI; ++i) wf[i] = *(const bf16x8*)(pw + i * 32 * 128 + xo[s]);
; #pragma unroll
;       for (int m = 0; m < NM; ++m) {
;         const int i = m / MJ, j = m % MJ;
;         acc[i][j] = MFMA(wf[i], af[j], acc[i][j]);
;         if (s < 2 && NM >= PPS) {
;           constexpr int EVERY = (NM / PPS) > 0 ? (NM / PPS) : 1;
;           if ((m + 1) % EVERY == 0) {
;             const int pc = s * PPS + (m + 1) / EVERY - 1;
;             if ((m + 1) / EVERY <= PPS && pc < NLD) {
;               __builtin_amdgcn_sched_barrier(0);
;               if (pre) issue_piece(kt + DIST, pc);
;               __builtin_amdgcn_sched_barrier(0);
;             }
;           }
;         }
;         if (s < 2 && NM < PPS) {
;           const int slot = s * NM + m;
;           __builtin_amdgcn_sched_barrier(0);
; #pragma unroll
;           for (int pc = 0; pc < NLD; ++pc)
;             if ((pc * 2 * NM) / NLD == slot && pre) issue_piece(kt + DIST, pc);
;           __builtin_amdgcn_sched_barrier(0);
;         }
;       }
;     }
	s_waitcnt lgkmcnt(0)
	v_mfma_f32_32x32x16_bf16 v[48:63], v[186:189], v[190:193], v[48:63]
	v_mfma_f32_32x32x16_bf16 v[16:31], v[186:189], v[194:197], v[16:31]
	ds_read_b128 v[186:189], v132 offset:32768
	ds_read_b128 v[216:219], v136
	ds_read_b128 v[220:223], v136 offset:4096
	ds_read_b128 v[224:227], v132 offset:36864
	ds_read_b128 v[228:231], v132 offset:40960
	ds_read_b128 v[206:209], v132 offset:45056
	v_mfma_f32_32x32x16_bf16 v[32:47], v[198:201], v[190:193], v[32:47]
	v_mfma_f32_32x32x16_bf16 v[0:15], v[198:201], v[194:197], v[0:15]
	s_waitcnt lgkmcnt(0)
	v_mfma_f32_32x32x16_bf16 v[96:111], v[186:189], v[216:219], v[96:111]
	v_mfma_f32_32x32x16_bf16 v[64:79], v[186:189], v[220:223], v[64:79]
	v_lshl_add_u64 v[186:187], v[130:131], 0, s[0:1]
	s_mov_b32 m0, s8
	s_nop 0
	global_load_lds_dwordx4 v[186:187], off
	v_mfma_f32_32x32x16_bf16 v[112:127], v[224:227], v[216:219], v[112:127]
	v_mfma_f32_32x32x16_bf16 v[80:95], v[224:227], v[220:223], v[80:95]
	s_mov_b64 s[0:1], 0x5a000
	v_lshl_add_u64 v[186:187], v[130:131], 0, s[0:1]
	s_mov_b32 m0, s9
	s_nop 0
	global_load_lds_dwordx4 v[186:187], off
	v_mfma_f32_32x32x16_bf16 v[48:63], v[228:231], v[216:219], v[48:63]
	v_mfma_f32_32x32x16_bf16 v[16:31], v[228:231], v[220:223], v[16:31]
	s_mov_b64 s[2:3], 0x5c000
	v_lshl_add_u64 v[186:187], v[130:131], 0, s[2:3]
	s_mov_b32 m0, s10
	s_nop 0
	global_load_lds_dwordx4 v[186:187], off
	v_mfma_f32_32x32x16_bf16 v[32:47], v[206:209], v[216:219], v[32:47]
	v_mfma_f32_32x32x16_bf16 v[0:15], v[206:209], v[220:223], v[0:15]
	s_mov_b64 s[4:5], 0x5e000
	v_lshl_add_u64 v[186:187], v[130:131], 0, s[4:5]
	s_mov_b32 m0, s11
	s_nop 0
	global_load_lds_dwordx4 v[186:187], off
	ds_read_b128 v[186:189], v133 offset:32768
	ds_read_b128 v[190:193], v137
	ds_read_b128 v[194:197], v137 offset:4096
	ds_read_b128 v[198:201], v133 offset:36864
	ds_read_b128 v[202:205], v133 offset:40960
	ds_read_b128 v[232:235], v133 offset:45056
	s_waitcnt lgkmcnt(0)
	ds_read_b128 v[212:215], v135 offset:32768
	ds_read_b128 v[216:219], v140
	ds_read_b128 v[220:223], v140 offset:4096
	ds_read_b128 v[224:227], v135 offset:36864
	v_mfma_f32_32x32x16_bf16 v[96:111], v[186:189], v[190:193], v[96:111]
	v_mfma_f32_32x32x16_bf16 v[64:79], v[186:189], v[194:197], v[64:79]
	s_mov_b32 m0, s12
	s_nop 0
	global_load_lds_dwordx4 v[210:211], off
	v_mfma_f32_32x32x16_bf16 v[112:127], v[198:201], v[190:193], v[112:127]
	v_mfma_f32_32x32x16_bf16 v[80:95], v[198:201], v[194:197], v[80:95]
	v_lshl_add_u64 v[186:187], v[128:129], 0, s[0:1]
	s_mov_b32 m0, s13
	s_nop 0
	global_load_lds_dwordx4 v[186:187], off
	v_mfma_f32_32x32x16_bf16 v[48:63], v[202:205], v[190:193], v[48:63]
	v_mfma_f32_32x32x16_bf16 v[16:31], v[202:205], v[194:197], v[16:31]
	v_lshl_add_u64 v[186:187], v[128:129], 0, s[2:3]
	s_mov_b32 m0, s14
	s_nop 0
	global_load_lds_dwordx4 v[186:187], off
	v_mfma_f32_32x32x16_bf16 v[32:47], v[232:235], v[190:193], v[32:47]
	v_mfma_f32_32x32x16_bf16 v[0:15], v[232:235], v[194:197], v[0:15]
	v_lshl_add_u64 v[186:187], v[128:129], 0, s[4:5]
	s_mov_b32 m0, s15
	s_nop 0
	global_load_lds_dwordx4 v[186:187], off
	s_mov_b64 s[0:1], 0x60000
	v_lshl_add_u64 v[210:211], v[128:129], 0, s[0:1]
	s_waitcnt lgkmcnt(0)
	ds_read_b128 v[186:189], v135 offset:40960
	ds_read_b128 v[198:201], v135 offset:45056
	v_mfma_f32_32x32x16_bf16 v[96:111], v[212:215], v[216:219], v[96:111]
	v_mfma_f32_32x32x16_bf16 v[64:79], v[212:215], v[220:223], v[64:79]
	v_mfma_f32_32x32x16_bf16 v[112:127], v[224:227], v[216:219], v[112:127]
	v_mfma_f32_32x32x16_bf16 v[80:95], v[224:227], v[220:223], v[80:95]
	s_waitcnt lgkmcnt(0)
	ds_read_b128 v[212:215], v134 offset:32768
	ds_read_b128 v[190:193], v139
	ds_read_b128 v[194:197], v139 offset:4096
	ds_read_b128 v[224:227], v134 offset:36864
	v_mfma_f32_32x32x16_bf16 v[48:63], v[186:189], v[216:219], v[48:63]
	v_mfma_f32_32x32x16_bf16 v[16:31], v[186:189], v[220:223], v[16:31]
	v_mfma_f32_32x32x16_bf16 v[32:47], v[198:201], v[216:219], v[32:47]
	v_mfma_f32_32x32x16_bf16 v[0:15], v[198:201], v[220:223], v[0:15]
	s_waitcnt lgkmcnt(0)
	ds_read_b128 v[186:189], v134 offset:40960
	ds_read_b128 v[198:201], v134 offset:45056
	v_mfma_f32_32x32x16_bf16 v[96:111], v[212:215], v[190:193], v[96:111]
	v_mfma_f32_32x32x16_bf16 v[64:79], v[212:215], v[194:197], v[64:79]
	v_mfma_f32_32x32x16_bf16 v[112:127], v[224:227], v[190:193], v[112:127]
	v_mfma_f32_32x32x16_bf16 v[80:95], v[224:227], v[194:197], v[80:95]
	s_waitcnt vmcnt(0)
	s_barrier
; #define MFMA(a, b, c) __builtin_amdgcn_mfma_f32_32x32x16_bf16((a), (b), (c), 0, 0, 0)
;     ...
;   for (int kt = 0; kt < nk; ++kt) {
;     if (DIST == 2 && kt + 1 < nk) {
;       if (NLD == 6) asm volatile("s_waitcnt vmcnt(6)" ::: "memory");
;       else if (NLD == 5) asm volatile("s_waitcnt vmcnt(5)" ::: "memory");
;       else asm volatile("s_waitcnt vmcnt(8)" ::: "memory");
;     } else {
;       asm volatile("s_waitcnt vmcnt(0)" ::: "memory");
;     }
;     __builtin_amdgcn_s_barrier();
;     const bool pre = (kt + DIST < nk);
;     const char* base = smem + (kt % NSTG) * STAGE;
;     const char* pa = base + (wrow_act + r) * 128;
;     const char* pw = base + ABYTES + (wrow_w + r) * 128;
;     constexpr int NM = NI * MJ;
;     constexpr int PPS = (NLD + 1) / 2;
; #pragma unroll
;     for (int s = 0; s < 4; ++s) {
;       bf16x8 af[MJ], wf[NI];
; #pragma unroll
;       for (int j = 0; j < MJ; ++j) af[j] = *(const bf16x8*)(pa + j * 32 * 128 + xo[s]);
; #pragma unroll
;       for (int i = 0; i < NI; ++i) wf[i] = *(const bf16x8*)(pw + i * 32 * 128 + xo[s]);
; #pragma unroll
;       for (int m = 0; m < NM; ++m) {
;         const int i = m / MJ, j = m % MJ;
;         acc[i][j] = MFMA(wf[i], af[j], acc[i][j]);
;         if (s < 2 && NM >= PPS) {
;           constexpr int EVERY = (NM / PPS) > 0 ? (NM / PPS) : 1;
;           if ((m + 1) % EVERY == 0) {
;             const int pc = s * PPS + (m + 1) / EVERY - 1;
;             if ((m + 1) / EVERY <= PPS && pc < NLD) {
;               __builtin_amdgcn_sched_barrier(0);
;               if (pre) issue_piece(kt + DIST, pc);
;               __builtin_amdgcn_sched_barrier(0);
;             }
;           }
;         }
;         if (s < 2 && NM < PPS) {
;           const int slot = s * NM + m;
;           __builtin_amdgcn_sched_barrier(0);
; #pragma unroll
;           for (int pc = 0; pc < NLD; ++pc)
;             if ((pc * 2 * NM) / NLD == slot && pre) issue_piece(kt + DIST, pc);
;           __builtin_amdgcn_sched_barrier(0);
;         }
;       }
;     }
	s_waitcnt lgkmcnt(0)
	v_mfma_f32_32x32x16_bf16 v[48:63], v[186:189], v[190:193], v[48:63]
	v_mfma_f32_32x32x16_bf16 v[16:31], v[186:189], v[194:197], v[16:31]
	ds_read_b128 v[186:189], v138
	ds_read_b128 v[216:219], v142
	ds_read_b128 v[220:223], v142 offset:4096
	ds_read_b128 v[224:227], v138 offset:4096
	ds_read_b128 v[228:231], v138 offset:8192
	ds_read_b128 v[206:209], v138 offset:12288
	v_mfma_f32_32x32x16_bf16 v[32:47], v[198:201], v[190:193], v[32:47]
	v_mfma_f32_32x32x16_bf16 v[0:15], v[198:201], v[194:197], v[0:15]
	s_waitcnt lgkmcnt(0)
	v_mfma_f32_32x32x16_bf16 v[96:111], v[186:189], v[216:219], v[96:111]
	v_mfma_f32_32x32x16_bf16 v[64:79], v[186:189], v[220:223], v[64:79]
	v_lshl_add_u64 v[186:187], v[130:131], 0, s[0:1]
	v_readfirstlane_b32 s0, v184
	s_mov_b32 m0, s0
	s_nop 0
	global_load_lds_dwordx4 v[186:187], off
	v_mfma_f32_32x32x16_bf16 v[112:127], v[224:227], v[216:219], v[112:127]
	v_mfma_f32_32x32x16_bf16 v[80:95], v[224:227], v[220:223], v[80:95]
	s_mov_b64 s[6:7], 0x62000
	v_readfirstlane_b32 s1, v183
	v_lshl_add_u64 v[184:185], v[130:131], 0, s[6:7]
	s_mov_b32 m0, s1
	s_nop 0
	global_load_lds_dwordx4 v[184:185], off
	v_mfma_f32_32x32x16_bf16 v[48:63], v[228:231], v[216:219], v[48:63]
	v_mfma_f32_32x32x16_bf16 v[16:31], v[228:231], v[220:223], v[16:31]
	s_mov_b64 s[8:9], 0x64000
	v_readfirstlane_b32 s2, v182
	v_lshl_add_u64 v[184:185], v[130:131], 0, s[8:9]
	s_mov_b32 m0, s2
	s_nop 0
	global_load_lds_dwordx4 v[184:185], off
	v_mfma_f32_32x32x16_bf16 v[32:47], v[206:209], v[216:219], v[32:47]
	v_mfma_f32_32x32x16_bf16 v[0:15], v[206:209], v[220:223], v[0:15]
	s_mov_b64 s[10:11], 0x66000
	v_readfirstlane_b32 s3, v181
	v_lshl_add_u64 v[182:183], v[130:131], 0, s[10:11]
	s_mov_b32 m0, s3
	s_nop 0
	global_load_lds_dwordx4 v[182:183], off
	ds_read_b128 v[182:185], v144
	ds_read_b128 v[186:189], v151
	ds_read_b128 v[190:193], v151 offset:4096
	ds_read_b128 v[194:197], v144 offset:4096
	ds_read_b128 v[198:201], v144 offset:8192
	ds_read_b128 v[202:205], v144 offset:12288
	s_waitcnt lgkmcnt(0)
	v_mfma_f32_32x32x16_bf16 v[96:111], v[182:185], v[186:189], v[96:111]
	v_mfma_f32_32x32x16_bf16 v[64:79], v[182:185], v[190:193], v[64:79]
	v_readfirstlane_b32 s4, v162
	s_mov_b32 m0, s4
	s_nop 0
	global_load_lds_dwordx4 v[210:211], off
	v_mfma_f32_32x32x16_bf16 v[112:127], v[194:197], v[186:189], v[112:127]
	v_mfma_f32_32x32x16_bf16 v[80:95], v[194:197], v[190:193], v[80:95]
	v_readfirstlane_b32 s5, v165
	v_lshl_add_u64 v[182:183], v[128:129], 0, s[6:7]
	s_mov_b32 m0, s5
	s_nop 0
	global_load_lds_dwordx4 v[182:183], off
	v_mfma_f32_32x32x16_bf16 v[48:63], v[198:201], v[186:189], v[48:63]
	v_mfma_f32_32x32x16_bf16 v[16:31], v[198:201], v[190:193], v[16:31]
	v_readfirstlane_b32 s6, v164
	v_lshl_add_u64 v[182:183], v[128:129], 0, s[8:9]
	s_mov_b32 m0, s6
	s_nop 0
	global_load_lds_dwordx4 v[182:183], off
	v_mfma_f32_32x32x16_bf16 v[32:47], v[202:205], v[186:189], v[32:47]
	v_mfma_f32_32x32x16_bf16 v[0:15], v[202:205], v[190:193], v[0:15]
	v_readfirstlane_b32 s7, v163
	v_lshl_add_u64 v[164:165], v[128:129], 0, s[10:11]
	s_mov_b32 m0, s7
	s_nop 0
	global_load_lds_dwordx4 v[164:165], off
	ds_read_b128 v[162:165], v143
	ds_read_b128 v[182:185], v153
	ds_read_b128 v[212:215], v153 offset:4096
	ds_read_b128 v[216:219], v143 offset:4096
	s_mov_b64 s[8:9], 0x68000
	v_lshl_add_u64 v[202:203], v[128:129], 0, s[8:9]
	s_waitcnt lgkmcnt(0)
	v_mfma_f32_32x32x16_bf16 v[96:111], v[162:165], v[182:185], v[96:111]
	v_mfma_f32_32x32x16_bf16 v[64:79], v[162:165], v[212:215], v[64:79]
	ds_read_b128 v[162:165], v143 offset:8192
	ds_read_b128 v[190:193], v143 offset:12288
	v_mfma_f32_32x32x16_bf16 v[112:127], v[216:219], v[182:185], v[112:127]
	v_mfma_f32_32x32x16_bf16 v[80:95], v[216:219], v[212:215], v[80:95]
	s_waitcnt lgkmcnt(0)
	v_mfma_f32_32x32x16_bf16 v[48:63], v[162:165], v[182:185], v[48:63]
	v_mfma_f32_32x32x16_bf16 v[16:31], v[162:165], v[212:215], v[16:31]
	ds_read_b128 v[162:165], v141
	v_mfma_f32_32x32x16_bf16 v[32:47], v[190:193], v[182:185], v[32:47]
	ds_read_b128 v[182:185], v152
	ds_read_b128 v[186:189], v152 offset:4096
	ds_read_b128 v[216:219], v141 offset:4096
	v_mfma_f32_32x32x16_bf16 v[0:15], v[190:193], v[212:215], v[0:15]
	s_waitcnt lgkmcnt(0)
	v_mfma_f32_32x32x16_bf16 v[96:111], v[162:165], v[182:185], v[96:111]
	v_mfma_f32_32x32x16_bf16 v[64:79], v[162:165], v[186:189], v[64:79]
	ds_read_b128 v[162:165], v141 offset:8192
	ds_read_b128 v[190:193], v141 offset:12288
	v_mfma_f32_32x32x16_bf16 v[112:127], v[216:219], v[182:185], v[112:127]
	v_mfma_f32_32x32x16_bf16 v[80:95], v[216:219], v[186:189], v[80:95]
	s_waitcnt vmcnt(0)
	s_barrier
; #define MFMA(a, b, c) __builtin_amdgcn_mfma_f32_32x32x16_bf16((a), (b), (c), 0, 0, 0)
;     ...
;   for (int kt = 0; kt < nk; ++kt) {
;     if (DIST == 2 && kt + 1 < nk) {
;       if (NLD == 6) asm volatile("s_waitcnt vmcnt(6)" ::: "memory");
;       else if (NLD == 5) asm volatile("s_waitcnt vmcnt(5)" ::: "memory");
;       else asm volatile("s_waitcnt vmcnt(8)" ::: "memory");
;     } else {
;       asm volatile("s_waitcnt vmcnt(0)" ::: "memory");
;     }
;     __builtin_amdgcn_s_barrier();
;     const bool pre = (kt + DIST < nk);
;     const char* base = smem + (kt % NSTG) * STAGE;
;     const char* pa = base + (wrow_act + r) * 128;
;     const char* pw = base + ABYTES + (wrow_w + r) * 128;
;     constexpr int NM = NI * MJ;
;     constexpr int PPS = (NLD + 1) / 2;
; #pragma unroll
;     for (int s = 0; s < 4; ++s) {
;       bf16x8 af[MJ], wf[NI];
; #pragma unroll
;       for (int j = 0; j < MJ; ++j) af[j] = *(const bf16x8*)(pa + j * 32 * 128 + xo[s]);
; #pragma unroll
;       for (int i = 0; i < NI; ++i) wf[i] = *(const bf16x8*)(pw + i * 32 * 128 + xo[s]);
; #pragma unroll
;       for (int m = 0; m < NM; ++m) {
;         const int i = m / MJ, j = m % MJ;
;         acc[i][j] = MFMA(wf[i], af[j], acc[i][j]);
;         if (s < 2 && NM >= PPS) {
;           constexpr int EVERY = (NM / PPS) > 0 ? (NM / PPS) : 1;
;           if ((m + 1) % EVERY == 0) {
;             const int pc = s * PPS + (m + 1) / EVERY - 1;
;             if ((m + 1) / EVERY <= PPS && pc < NLD) {
;               __builtin_amdgcn_sched_barrier(0);
;               if (pre) issue_piece(kt + DIST, pc);
;               __builtin_amdgcn_sched_barrier(0);
;             }
;           }
;         }
;         if (s < 2 && NM < PPS) {
;           const int slot = s * NM + m;
;           __builtin_amdgcn_sched_barrier(0);
; #pragma unroll
;           for (int pc = 0; pc < NLD; ++pc)
;             if ((pc * 2 * NM) / NLD == slot && pre) issue_piece(kt + DIST, pc);
;           __builtin_amdgcn_sched_barrier(0);
;         }
;       }
;     }
	s_waitcnt lgkmcnt(0)
	v_mfma_f32_32x32x16_bf16 v[48:63], v[162:165], v[182:185], v[48:63]
	v_mfma_f32_32x32x16_bf16 v[16:31], v[162:165], v[186:189], v[16:31]
	ds_read_b128 v[162:165], v132 offset:32768
	v_mfma_f32_32x32x16_bf16 v[32:47], v[190:193], v[182:185], v[32:47]
	ds_read_b128 v[182:185], v136
	ds_read_b128 v[212:215], v136 offset:4096
	ds_read_b128 v[216:219], v132 offset:36864
	ds_read_b128 v[220:223], v132 offset:40960
	ds_read_b128 v[224:227], v132 offset:45056
	v_mfma_f32_32x32x16_bf16 v[0:15], v[190:193], v[186:189], v[0:15]
	s_waitcnt lgkmcnt(0)
	v_mfma_f32_32x32x16_bf16 v[96:111], v[162:165], v[182:185], v[96:111]
	v_mfma_f32_32x32x16_bf16 v[64:79], v[162:165], v[212:215], v[64:79]
	v_lshl_add_u64 v[162:163], v[130:131], 0, s[8:9]
	v_readfirstlane_b32 s8, v155
	s_mov_b32 m0, s8
	s_nop 0
	global_load_lds_dwordx4 v[162:163], off
	v_mfma_f32_32x32x16_bf16 v[112:127], v[216:219], v[182:185], v[112:127]
	v_mfma_f32_32x32x16_bf16 v[80:95], v[216:219], v[212:215], v[80:95]
	s_mov_b64 s[14:15], 0x6a000
	v_readfirstlane_b32 s9, v158
	v_lshl_add_u64 v[162:163], v[130:131], 0, s[14:15]
	s_mov_b32 m0, s9
	s_nop 0
	global_load_lds_dwordx4 v[162:163], off
	v_mfma_f32_32x32x16_bf16 v[48:63], v[220:223], v[182:185], v[48:63]
	v_mfma_f32_32x32x16_bf16 v[16:31], v[220:223], v[212:215], v[16:31]
	s_mov_b64 s[16:17], 0x6c000
	v_readfirstlane_b32 s10, v157
	v_lshl_add_u64 v[162:163], v[130:131], 0, s[16:17]
	s_mov_b32 m0, s10
	s_nop 0
	global_load_lds_dwordx4 v[162:163], off
	v_mfma_f32_32x32x16_bf16 v[32:47], v[224:227], v[182:185], v[32:47]
	v_mfma_f32_32x32x16_bf16 v[0:15], v[224:227], v[212:215], v[0:15]
	s_mov_b64 s[18:19], 0x6e000
	v_readfirstlane_b32 s11, v156
	v_lshl_add_u64 v[162:163], v[130:131], 0, s[18:19]
	s_mov_b32 m0, s11
	s_nop 0
	global_load_lds_dwordx4 v[162:163], off
	ds_read_b128 v[162:165], v133 offset:32768
	ds_read_b128 v[182:185], v137
	ds_read_b128 v[186:189], v137 offset:4096
	ds_read_b128 v[190:193], v133 offset:36864
	ds_read_b128 v[194:197], v133 offset:40960
	ds_read_b128 v[198:201], v133 offset:45056
	s_waitcnt lgkmcnt(0)
	v_mfma_f32_32x32x16_bf16 v[96:111], v[162:165], v[182:185], v[96:111]
	v_mfma_f32_32x32x16_bf16 v[64:79], v[162:165], v[186:189], v[64:79]
	v_readfirstlane_b32 s12, v154
	s_mov_b32 m0, s12
	s_nop 0
	global_load_lds_dwordx4 v[202:203], off
	v_mfma_f32_32x32x16_bf16 v[112:127], v[190:193], v[182:185], v[112:127]
	v_mfma_f32_32x32x16_bf16 v[80:95], v[190:193], v[186:189], v[80:95]
	v_readfirstlane_b32 s13, v159
	v_lshl_add_u64 v[154:155], v[128:129], 0, s[14:15]
	s_mov_b32 m0, s13
	s_nop 0
	global_load_lds_dwordx4 v[154:155], off
	v_mfma_f32_32x32x16_bf16 v[48:63], v[194:197], v[182:185], v[48:63]
	v_mfma_f32_32x32x16_bf16 v[16:31], v[194:197], v[186:189], v[16:31]
	v_readfirstlane_b32 s14, v160
	v_lshl_add_u64 v[154:155], v[128:129], 0, s[16:17]
	s_mov_b32 m0, s14
	s_nop 0
	global_load_lds_dwordx4 v[154:155], off
	v_mfma_f32_32x32x16_bf16 v[32:47], v[198:201], v[182:185], v[32:47]
	v_mfma_f32_32x32x16_bf16 v[0:15], v[198:201], v[186:189], v[0:15]
	v_readfirstlane_b32 s15, v161
	v_lshl_add_u64 v[154:155], v[128:129], 0, s[18:19]
	s_mov_b32 m0, s15
	s_nop 0
	global_load_lds_dwordx4 v[154:155], off
	ds_read_b128 v[154:157], v135 offset:32768
	ds_read_b128 v[158:161], v140
	ds_read_b128 v[162:165], v140 offset:4096
	ds_read_b128 v[182:185], v135 offset:36864
	s_mov_b64 s[16:17], 0x70000
	v_lshl_add_u64 v[194:195], v[128:129], 0, s[16:17]
	s_waitcnt lgkmcnt(0)
	v_mfma_f32_32x32x16_bf16 v[96:111], v[154:157], v[158:161], v[96:111]
	v_mfma_f32_32x32x16_bf16 v[64:79], v[154:157], v[162:165], v[64:79]
	ds_read_b128 v[154:157], v135 offset:40960
	v_mfma_f32_32x32x16_bf16 v[112:127], v[182:185], v[158:161], v[112:127]
	v_mfma_f32_32x32x16_bf16 v[80:95], v[182:185], v[162:165], v[80:95]
	ds_read_b128 v[182:185], v135 offset:45056
	s_waitcnt lgkmcnt(0)
	v_mfma_f32_32x32x16_bf16 v[48:63], v[154:157], v[158:161], v[48:63]
	v_mfma_f32_32x32x16_bf16 v[16:31], v[154:157], v[162:165], v[16:31]
	ds_read_b128 v[154:157], v134 offset:32768
	v_mfma_f32_32x32x16_bf16 v[32:47], v[182:185], v[158:161], v[32:47]
	ds_read_b128 v[158:161], v139
	v_mfma_f32_32x32x16_bf16 v[0:15], v[182:185], v[162:165], v[0:15]
	ds_read_b128 v[162:165], v139 offset:4096
	ds_read_b128 v[182:185], v134 offset:36864
	s_waitcnt lgkmcnt(0)
	v_mfma_f32_32x32x16_bf16 v[96:111], v[154:157], v[158:161], v[96:111]
	v_mfma_f32_32x32x16_bf16 v[64:79], v[154:157], v[162:165], v[64:79]
	ds_read_b128 v[154:157], v134 offset:40960
	v_mfma_f32_32x32x16_bf16 v[112:127], v[182:185], v[158:161], v[112:127]
	v_mfma_f32_32x32x16_bf16 v[80:95], v[182:185], v[162:165], v[80:95]
	ds_read_b128 v[182:185], v134 offset:45056
	s_waitcnt vmcnt(0)
	s_barrier
; #define MFMA(a, b, c) __builtin_amdgcn_mfma_f32_32x32x16_bf16((a), (b), (c), 0, 0, 0)
;     ...
;   for (int kt = 0; kt < nk; ++kt) {
;     if (DIST == 2 && kt + 1 < nk) {
;       if (NLD == 6) asm volatile("s_waitcnt vmcnt(6)" ::: "memory");
;       else if (NLD == 5) asm volatile("s_waitcnt vmcnt(5)" ::: "memory");
;       else asm volatile("s_waitcnt vmcnt(8)" ::: "memory");
;     } else {
;       asm volatile("s_waitcnt vmcnt(0)" ::: "memory");
;     }
;     __builtin_amdgcn_s_barrier();
;     const bool pre = (kt + DIST < nk);
;     const char* base = smem + (kt % NSTG) * STAGE;
;     const char* pa = base + (wrow_act + r) * 128;
;     const char* pw = base + ABYTES + (wrow_w + r) * 128;
;     constexpr int NM = NI * MJ;
;     constexpr int PPS = (NLD + 1) / 2;
; #pragma unroll
;     for (int s = 0; s < 4; ++s) {
;       bf16x8 af[MJ], wf[NI];
; #pragma unroll
;       for (int j = 0; j < MJ; ++j) af[j] = *(const bf16x8*)(pa + j * 32 * 128 + xo[s]);
; #pragma unroll
;       for (int i = 0; i < NI; ++i) wf[i] = *(const bf16x8*)(pw + i * 32 * 128 + xo[s]);
; #pragma unroll
;       for (int m = 0; m < NM; ++m) {
;         const int i = m / MJ, j = m % MJ;
;         acc[i][j] = MFMA(wf[i], af[j], acc[i][j]);
;         if (s < 2 && NM >= PPS) {
;           constexpr int EVERY = (NM / PPS) > 0 ? (NM / PPS) : 1;
;           if ((m + 1) % EVERY == 0) {
;             const int pc = s * PPS + (m + 1) / EVERY - 1;
;             if ((m + 1) / EVERY <= PPS && pc < NLD) {
;               __builtin_amdgcn_sched_barrier(0);
;               if (pre) issue_piece(kt + DIST, pc);
;               __builtin_amdgcn_sched_barrier(0);
;             }
;           }
;         }
;         if (s < 2 && NM < PPS) {
;           const int slot = s * NM + m;
;           __builtin_amdgcn_sched_barrier(0);
; #pragma unroll
;           for (int pc = 0; pc < NLD; ++pc)
;             if ((pc * 2 * NM) / NLD == slot && pre) issue_piece(kt + DIST, pc);
;           __builtin_amdgcn_sched_barrier(0);
;         }
;       }
;     }
	s_waitcnt lgkmcnt(0)
	v_mfma_f32_32x32x16_bf16 v[48:63], v[154:157], v[158:161], v[48:63]
	v_mfma_f32_32x32x16_bf16 v[16:31], v[154:157], v[162:165], v[16:31]
	ds_read_b128 v[154:157], v138
	v_mfma_f32_32x32x16_bf16 v[32:47], v[182:185], v[158:161], v[32:47]
	ds_read_b128 v[158:161], v142
	v_mfma_f32_32x32x16_bf16 v[0:15], v[182:185], v[162:165], v[0:15]
	ds_read_b128 v[162:165], v142 offset:4096
	ds_read_b128 v[182:185], v138 offset:4096
	ds_read_b128 v[212:215], v138 offset:8192
	ds_read_b128 v[216:219], v138 offset:12288
	s_waitcnt lgkmcnt(0)
	v_mfma_f32_32x32x16_bf16 v[96:111], v[154:157], v[158:161], v[96:111]
	v_mfma_f32_32x32x16_bf16 v[64:79], v[154:157], v[162:165], v[64:79]
	v_lshl_add_u64 v[154:155], v[130:131], 0, s[16:17]
	s_mov_b32 m0, s0
	s_nop 0
	global_load_lds_dwordx4 v[154:155], off
	v_mfma_f32_32x32x16_bf16 v[112:127], v[182:185], v[158:161], v[112:127]
	v_mfma_f32_32x32x16_bf16 v[80:95], v[182:185], v[162:165], v[80:95]
	s_mov_b64 s[16:17], 0x72000
	v_lshl_add_u64 v[154:155], v[130:131], 0, s[16:17]
	s_mov_b32 m0, s1
	s_nop 0
	global_load_lds_dwordx4 v[154:155], off
	v_mfma_f32_32x32x16_bf16 v[48:63], v[212:215], v[158:161], v[48:63]
	v_mfma_f32_32x32x16_bf16 v[16:31], v[212:215], v[162:165], v[16:31]
	s_mov_b64 s[0:1], 0x74000
	v_lshl_add_u64 v[154:155], v[130:131], 0, s[0:1]
	s_mov_b32 m0, s2
	s_nop 0
	global_load_lds_dwordx4 v[154:155], off
	v_mfma_f32_32x32x16_bf16 v[32:47], v[216:219], v[158:161], v[32:47]
	v_mfma_f32_32x32x16_bf16 v[0:15], v[216:219], v[162:165], v[0:15]
	s_mov_b64 s[18:19], 0x76000
	v_lshl_add_u64 v[154:155], v[130:131], 0, s[18:19]
	s_mov_b32 m0, s3
	s_nop 0
	global_load_lds_dwordx4 v[154:155], off
	ds_read_b128 v[154:157], v144
	ds_read_b128 v[158:161], v151
	ds_read_b128 v[162:165], v151 offset:4096
	ds_read_b128 v[182:185], v144 offset:4096
	ds_read_b128 v[186:189], v144 offset:8192
	ds_read_b128 v[190:193], v144 offset:12288
	s_waitcnt lgkmcnt(0)
	v_mfma_f32_32x32x16_bf16 v[96:111], v[154:157], v[158:161], v[96:111]
	v_mfma_f32_32x32x16_bf16 v[64:79], v[154:157], v[162:165], v[64:79]
	s_mov_b32 m0, s4
	s_nop 0
	global_load_lds_dwordx4 v[194:195], off
	v_mfma_f32_32x32x16_bf16 v[112:127], v[182:185], v[158:161], v[112:127]
	v_mfma_f32_32x32x16_bf16 v[80:95], v[182:185], v[162:165], v[80:95]
	v_lshl_add_u64 v[154:155], v[128:129], 0, s[16:17]
	s_mov_b32 m0, s5
	s_nop 0
	global_load_lds_dwordx4 v[154:155], off
	v_mfma_f32_32x32x16_bf16 v[48:63], v[186:189], v[158:161], v[48:63]
	v_mfma_f32_32x32x16_bf16 v[16:31], v[186:189], v[162:165], v[16:31]
	v_lshl_add_u64 v[154:155], v[128:129], 0, s[0:1]
	s_mov_b32 m0, s6
	s_nop 0
	global_load_lds_dwordx4 v[154:155], off
	v_mfma_f32_32x32x16_bf16 v[32:47], v[190:193], v[158:161], v[32:47]
	v_mfma_f32_32x32x16_bf16 v[0:15], v[190:193], v[162:165], v[0:15]
	v_lshl_add_u64 v[154:155], v[128:129], 0, s[18:19]
	s_mov_b32 m0, s7
	s_nop 0
	global_load_lds_dwordx4 v[154:155], off
	ds_read_b128 v[154:157], v143
	ds_read_b128 v[158:161], v153
	ds_read_b128 v[162:165], v153 offset:4096
	ds_read_b128 v[182:185], v143 offset:4096
	s_mov_b64 s[0:1], 0x78000
	v_lshl_add_u64 v[194:195], v[128:129], 0, s[0:1]
	s_waitcnt lgkmcnt(0)
	v_mfma_f32_32x32x16_bf16 v[96:111], v[154:157], v[158:161], v[96:111]
	v_mfma_f32_32x32x16_bf16 v[64:79], v[154:157], v[162:165], v[64:79]
	ds_read_b128 v[154:157], v143 offset:8192
	v_mfma_f32_32x32x16_bf16 v[112:127], v[182:185], v[158:161], v[112:127]
	v_mfma_f32_32x32x16_bf16 v[80:95], v[182:185], v[162:165], v[80:95]
	ds_read_b128 v[182:185], v143 offset:12288
	s_waitcnt lgkmcnt(0)
	v_mfma_f32_32x32x16_bf16 v[48:63], v[154:157], v[158:161], v[48:63]
	v_mfma_f32_32x32x16_bf16 v[16:31], v[154:157], v[162:165], v[16:31]
	ds_read_b128 v[154:157], v141
	v_mfma_f32_32x32x16_bf16 v[32:47], v[182:185], v[158:161], v[32:47]
	ds_read_b128 v[158:161], v152
	v_mfma_f32_32x32x16_bf16 v[0:15], v[182:185], v[162:165], v[0:15]
	ds_read_b128 v[162:165], v152 offset:4096
	ds_read_b128 v[182:185], v141 offset:4096
	s_waitcnt lgkmcnt(0)
	v_mfma_f32_32x32x16_bf16 v[96:111], v[154:157], v[158:161], v[96:111]
	v_mfma_f32_32x32x16_bf16 v[64:79], v[154:157], v[162:165], v[64:79]
	ds_read_b128 v[154:157], v141 offset:8192
	v_mfma_f32_32x32x16_bf16 v[112:127], v[182:185], v[158:161], v[112:127]
	v_mfma_f32_32x32x16_bf16 v[80:95], v[182:185], v[162:165], v[80:95]
	ds_read_b128 v[182:185], v141 offset:12288
	s_waitcnt vmcnt(0)
	s_barrier
; #define MFMA(a, b, c) __builtin_amdgcn_mfma_f32_32x32x16_bf16((a), (b), (c), 0, 0, 0)
;     ...
;   for (int kt = 0; kt < nk; ++kt) {
;     if (DIST == 2 && kt + 1 < nk) {
;       if (NLD == 6) asm volatile("s_waitcnt vmcnt(6)" ::: "memory");
;       else if (NLD == 5) asm volatile("s_waitcnt vmcnt(5)" ::: "memory");
;       else asm volatile("s_waitcnt vmcnt(8)" ::: "memory");
;     } else {
;       asm volatile("s_waitcnt vmcnt(0)" ::: "memory");
;     }
;     __builtin_amdgcn_s_barrier();
;     const bool pre = (kt + DIST < nk);
;     const char* base = smem + (kt % NSTG) * STAGE;
;     const char* pa = base + (wrow_act + r) * 128;
;     const char* pw = base + ABYTES + (wrow_w + r) * 128;
;     constexpr int NM = NI * MJ;
;     constexpr int PPS = (NLD + 1) / 2;
; #pragma unroll
;     for (int s = 0; s < 4; ++s) {
;       bf16x8 af[MJ], wf[NI];
; #pragma unroll
;       for (int j = 0; j < MJ; ++j) af[j] = *(const bf16x8*)(pa + j * 32 * 128 + xo[s]);
; #pragma unroll
;       for (int i = 0; i < NI; ++i) wf[i] = *(const bf16x8*)(pw + i * 32 * 128 + xo[s]);
; #pragma unroll
;       for (int m = 0; m < NM; ++m) {
;         const int i = m / MJ, j = m % MJ;
;         acc[i][j] = MFMA(wf[i], af[j], acc[i][j]);
;         if (s < 2 && NM >= PPS) {
;           constexpr int EVERY = (NM / PPS) > 0 ? (NM / PPS) : 1;
;           if ((m + 1) % EVERY == 0) {
;             const int pc = s * PPS + (m + 1) / EVERY - 1;
;             if ((m + 1) / EVERY <= PPS && pc < NLD) {
;               __builtin_amdgcn_sched_barrier(0);
;               if (pre) issue_piece(kt + DIST, pc);
;               __builtin_amdgcn_sched_barrier(0);
;             }
;           }
;         }
;         if (s < 2 && NM < PPS) {
;           const int slot = s * NM + m;
;           __builtin_amdgcn_sched_barrier(0);
; #pragma unroll
;           for (int pc = 0; pc < NLD; ++pc)
;             if ((pc * 2 * NM) / NLD == slot && pre) issue_piece(kt + DIST, pc);
;           __builtin_amdgcn_sched_barrier(0);
;         }
;       }
;     }
	s_waitcnt lgkmcnt(0)
	v_mfma_f32_32x32x16_bf16 v[48:63], v[154:157], v[158:161], v[48:63]
	v_mfma_f32_32x32x16_bf16 v[16:31], v[154:157], v[162:165], v[16:31]
	ds_read_b128 v[154:157], v132 offset:32768
	v_mfma_f32_32x32x16_bf16 v[32:47], v[182:185], v[158:161], v[32:47]
	ds_read_b128 v[158:161], v136
	v_mfma_f32_32x32x16_bf16 v[0:15], v[182:185], v[162:165], v[0:15]
	ds_read_b128 v[162:165], v136 offset:4096
	ds_read_b128 v[182:185], v132 offset:36864
	ds_read_b128 v[212:215], v132 offset:40960
	ds_read_b128 v[216:219], v132 offset:45056
	s_waitcnt lgkmcnt(0)
	v_mfma_f32_32x32x16_bf16 v[96:111], v[154:157], v[158:161], v[96:111]
	v_mfma_f32_32x32x16_bf16 v[64:79], v[154:157], v[162:165], v[64:79]
	v_lshl_add_u64 v[154:155], v[130:131], 0, s[0:1]
	s_mov_b32 m0, s8
	s_nop 0
	global_load_lds_dwordx4 v[154:155], off
	v_mfma_f32_32x32x16_bf16 v[112:127], v[182:185], v[158:161], v[112:127]
	v_mfma_f32_32x32x16_bf16 v[80:95], v[182:185], v[162:165], v[80:95]
	s_mov_b64 s[0:1], 0x7a000
	v_lshl_add_u64 v[154:155], v[130:131], 0, s[0:1]
	s_mov_b32 m0, s9
	s_nop 0
	global_load_lds_dwordx4 v[154:155], off
	v_mfma_f32_32x32x16_bf16 v[48:63], v[212:215], v[158:161], v[48:63]
	v_mfma_f32_32x32x16_bf16 v[16:31], v[212:215], v[162:165], v[16:31]
	s_mov_b64 s[2:3], 0x7c000
	v_lshl_add_u64 v[154:155], v[130:131], 0, s[2:3]
	s_mov_b32 m0, s10
	s_nop 0
	global_load_lds_dwordx4 v[154:155], off
	ds_read_b128 v[154:157], v133 offset:32768
	v_mfma_f32_32x32x16_bf16 v[32:47], v[216:219], v[158:161], v[32:47]
	ds_read_b128 v[158:161], v137
	v_mfma_f32_32x32x16_bf16 v[0:15], v[216:219], v[162:165], v[0:15]
	s_mov_b64 s[4:5], 0x7e000
	v_lshl_add_u64 v[130:131], v[130:131], 0, s[4:5]
	s_mov_b32 m0, s11
	s_nop 0
	global_load_lds_dwordx4 v[130:131], off
	ds_read_b128 v[162:165], v137 offset:4096
	ds_read_b128 v[182:185], v133 offset:36864
	ds_read_b128 v[186:189], v133 offset:40960
	ds_read_b128 v[130:133], v133 offset:45056
	s_waitcnt lgkmcnt(0)
	v_mfma_f32_32x32x16_bf16 v[96:111], v[154:157], v[158:161], v[96:111]
	v_mfma_f32_32x32x16_bf16 v[64:79], v[154:157], v[162:165], v[64:79]
	s_mov_b32 m0, s12
	s_nop 0
	global_load_lds_dwordx4 v[194:195], off
	v_mfma_f32_32x32x16_bf16 v[112:127], v[182:185], v[158:161], v[112:127]
	v_mfma_f32_32x32x16_bf16 v[80:95], v[182:185], v[162:165], v[80:95]
	v_lshl_add_u64 v[136:137], v[128:129], 0, s[0:1]
	s_mov_b32 m0, s13
	s_nop 0
	global_load_lds_dwordx4 v[136:137], off
	v_mfma_f32_32x32x16_bf16 v[48:63], v[186:189], v[158:161], v[48:63]
	v_mfma_f32_32x32x16_bf16 v[16:31], v[186:189], v[162:165], v[16:31]
	v_lshl_add_u64 v[136:137], v[128:129], 0, s[2:3]
	s_mov_b32 m0, s14
	s_nop 0
	global_load_lds_dwordx4 v[136:137], off
	v_mfma_f32_32x32x16_bf16 v[32:47], v[130:133], v[158:161], v[32:47]
	v_mfma_f32_32x32x16_bf16 v[0:15], v[130:133], v[162:165], v[0:15]
	v_lshl_add_u64 v[128:129], v[128:129], 0, s[4:5]
	s_mov_b32 m0, s15
	s_nop 0
	global_load_lds_dwordx4 v[128:129], off
	ds_read_b128 v[128:131], v135 offset:32768
	ds_read_b128 v[154:157], v140
	ds_read_b128 v[158:161], v140 offset:4096
	ds_read_b128 v[162:165], v135 offset:36864
	s_waitcnt lgkmcnt(0)
	v_mfma_f32_32x32x16_bf16 v[96:111], v[128:131], v[154:157], v[96:111]
	v_mfma_f32_32x32x16_bf16 v[64:79], v[128:131], v[158:161], v[64:79]
	ds_read_b128 v[128:131], v135 offset:40960
	v_mfma_f32_32x32x16_bf16 v[112:127], v[162:165], v[154:157], v[112:127]
	v_mfma_f32_32x32x16_bf16 v[80:95], v[162:165], v[158:161], v[80:95]
	ds_read_b128 v[162:165], v135 offset:45056
	s_waitcnt lgkmcnt(0)
	v_mfma_f32_32x32x16_bf16 v[48:63], v[128:131], v[154:157], v[48:63]
	v_mfma_f32_32x32x16_bf16 v[16:31], v[128:131], v[158:161], v[16:31]
	ds_read_b128 v[128:131], v134 offset:32768
	v_mfma_f32_32x32x16_bf16 v[32:47], v[162:165], v[154:157], v[32:47]
	ds_read_b128 v[154:157], v139
	v_mfma_f32_32x32x16_bf16 v[0:15], v[162:165], v[158:161], v[0:15]
	ds_read_b128 v[158:161], v139 offset:4096
	ds_read_b128 v[162:165], v134 offset:36864
	s_waitcnt lgkmcnt(0)
	v_mfma_f32_32x32x16_bf16 v[96:111], v[128:131], v[154:157], v[96:111]
	v_mfma_f32_32x32x16_bf16 v[64:79], v[128:131], v[158:161], v[64:79]
	ds_read_b128 v[128:131], v134 offset:40960
	ds_read_b128 v[132:135], v134 offset:45056
	s_waitcnt vmcnt(0)
	s_barrier
; #define MFMA(a, b, c) __builtin_amdgcn_mfma_f32_32x32x16_bf16((a), (b), (c), 0, 0, 0)
;     ...
; #pragma unroll
;     for (int s = 0; s < 4; ++s) {
;       bf16x8 af[MJ], wf[NI];
; #pragma unroll
;       for (int j = 0; j < MJ; ++j) af[j] = *(const bf16x8*)(pa + j * 32 * 128 + xo[s]);
; #pragma unroll
;       for (int i = 0; i < NI; ++i) wf[i] = *(const bf16x8*)(pw + i * 32 * 128 + xo[s]);
; #pragma unroll
;       for (int m = 0; m < NM; ++m) {
;         const int i = m / MJ, j = m % MJ;
;         acc[i][j] = MFMA(wf[i], af[j], acc[i][j]);
;         if (s < 2 && NM >= PPS) {
;           constexpr int EVERY = (NM / PPS) > 0 ? (NM / PPS) : 1;
;           if ((m + 1) % EVERY == 0) {
;             const int pc = s * PPS + (m + 1) / EVERY - 1;
;             if ((m + 1) / EVERY <= PPS && pc < NLD) {
;               __builtin_amdgcn_sched_barrier(0);
;               if (pre) issue_piece(kt + DIST, pc);
;               __builtin_amdgcn_sched_barrier(0);
;             }
;           }
;         }
;         if (s < 2 && NM < PPS) {
;           const int slot = s * NM + m;
;           __builtin_amdgcn_sched_barrier(0);
; #pragma unroll
;           for (int pc = 0; pc < NLD; ++pc)
;             if ((pc * 2 * NM) / NLD == slot && pre) issue_piece(kt + DIST, pc);
;           __builtin_amdgcn_sched_barrier(0);
;         }
;       }
;     }
;   }
;   __builtin_amdgcn_s_barrier();
; DEV void inproj_epilogue(f32x16 (&acc)[2][2], int fb, int m0w, const Params& p, int l) {
;     ...
;   int mode = 0;
;   int ssq_slot = -1;
;   u16* dst;
;   size_t pitch;
;   int col0;
;   bool headmajor = false;
;   int hm_heads = 0, hm_head = 0, hm_w = 0;
;   if (fb < 24) { headmajor = true; dst = (u16*)(ws + OFF_NAV); hm_heads = 8; hm_head = fb - 16; hm_w = 64; col0 = 0; pitch = 0; }
;   else if (fb < 30) { dst = (u16*)(ws + OFF_CQ); pitch = 384; col0 = (fb - 24) * 64; ssq_slot = fb - 24; }
;   else if (fb < 34) { dst = (u16*)(ws + OFF_CKV); pitch = 256; col0 = (fb - 30) * 64; ssq_slot = 6 + fb - 30; }
;   else if (fb < 60) { headmajor = true; dst = (u16*)(ws + OFF_DV); hm_heads = 4; hm_head = (fb - 52) >> 1; hm_w = 128; col0 = ((fb - 52) & 1) * 64; pitch = 0; }
;   else if (fb < 84) { dst = (u16*)(ws + OFF_Z); pitch = 1536; col0 = (fb - 60) * 64; mode = 1; }
;   else { dst = (u16*)(ws + OFF_G); pitch = 3072; col0 = (fb - 84) * 64; mode = 2; }
	v_mfma_f32_32x32x16_bf16 v[112:127], v[162:165], v[154:157], v[112:127]
	v_mfma_f32_32x32x16_bf16 v[80:95], v[162:165], v[158:161], v[80:95]
	s_waitcnt lgkmcnt(0)
	v_mfma_f32_32x32x16_bf16 v[48:63], v[128:131], v[154:157], v[48:63]
	v_mfma_f32_32x32x16_bf16 v[16:31], v[128:131], v[158:161], v[16:31]
	ds_read_b128 v[128:131], v138
	v_mfma_f32_32x32x16_bf16 v[32:47], v[132:135], v[154:157], v[32:47]
	v_mfma_f32_32x32x16_bf16 v[0:15], v[132:135], v[158:161], v[0:15]
	ds_read_b128 v[132:135], v142
	ds_read_b128 v[154:157], v142 offset:4096
	ds_read_b128 v[158:161], v138 offset:4096
	ds_read_b128 v[162:165], v138 offset:8192
	ds_read_b128 v[136:139], v138 offset:12288
	s_waitcnt lgkmcnt(0)
	v_mfma_f32_32x32x16_bf16 v[96:111], v[128:131], v[132:135], v[96:111]
	v_mfma_f32_32x32x16_bf16 v[64:79], v[128:131], v[154:157], v[64:79]
	ds_read_b128 v[128:131], v144
	v_mfma_f32_32x32x16_bf16 v[112:127], v[158:161], v[132:135], v[112:127]
	v_mfma_f32_32x32x16_bf16 v[80:95], v[158:161], v[154:157], v[80:95]
	v_mfma_f32_32x32x16_bf16 v[48:63], v[162:165], v[132:135], v[48:63]
	v_mfma_f32_32x32x16_bf16 v[16:31], v[162:165], v[154:157], v[16:31]
	v_mfma_f32_32x32x16_bf16 v[32:47], v[136:139], v[132:135], v[32:47]
	ds_read_b128 v[132:135], v151
	v_mfma_f32_32x32x16_bf16 v[0:15], v[136:139], v[154:157], v[0:15]
	ds_read_b128 v[136:139], v151 offset:4096
	ds_read_b128 v[154:157], v144 offset:4096
	ds_read_b128 v[158:161], v144 offset:8192
	ds_read_b128 v[162:165], v144 offset:12288
	s_waitcnt lgkmcnt(0)
	v_mfma_f32_32x32x16_bf16 v[96:111], v[128:131], v[132:135], v[96:111]
	v_mfma_f32_32x32x16_bf16 v[64:79], v[128:131], v[136:139], v[64:79]
	ds_read_b128 v[128:131], v143
	v_mfma_f32_32x32x16_bf16 v[112:127], v[154:157], v[132:135], v[112:127]
	v_mfma_f32_32x32x16_bf16 v[80:95], v[154:157], v[136:139], v[80:95]
	v_mfma_f32_32x32x16_bf16 v[48:63], v[158:161], v[132:135], v[48:63]
	v_mfma_f32_32x32x16_bf16 v[16:31], v[158:161], v[136:139], v[16:31]
	v_mfma_f32_32x32x16_bf16 v[32:47], v[162:165], v[132:135], v[32:47]
	ds_read_b128 v[132:135], v153
	v_mfma_f32_32x32x16_bf16 v[0:15], v[162:165], v[136:139], v[0:15]
	ds_read_b128 v[136:139], v153 offset:4096
	s_lshl_b32 s27, s50, 2
	v_readlane_b32 s0, v242, 1
	v_readlane_b32 s2, v242, 3
	s_waitcnt lgkmcnt(0)
	v_mfma_f32_32x32x16_bf16 v[96:111], v[128:131], v[132:135], v[96:111]
	v_readlane_b32 s3, v242, 4
	v_readlane_b32 s6, v242, 7
	v_readlane_b32 s7, v242, 8
	v_readlane_b32 s1, v242, 2
	s_mov_b64 s[2:3], s[6:7]
	v_lshl_add_u32 v151, s52, 8, v146
	v_readlane_b32 s4, v242, 5
	v_mfma_f32_32x32x16_bf16 v[64:79], v[128:131], v[136:139], v[64:79]
	ds_read_b128 v[128:131], v143 offset:4096
	v_readlane_b32 s5, v242, 6
	s_waitcnt lgkmcnt(0)
	v_mfma_f32_32x32x16_bf16 v[112:127], v[128:131], v[132:135], v[112:127]
	v_mfma_f32_32x32x16_bf16 v[80:95], v[128:131], v[136:139], v[80:95]
	ds_read_b128 v[128:131], v143 offset:8192
	s_waitcnt lgkmcnt(0)
	v_mfma_f32_32x32x16_bf16 v[48:63], v[128:131], v[132:135], v[48:63]
	v_mfma_f32_32x32x16_bf16 v[16:31], v[128:131], v[136:139], v[16:31]
	ds_read_b128 v[128:131], v143 offset:12288
	s_waitcnt lgkmcnt(0)
	v_mfma_f32_32x32x16_bf16 v[32:47], v[128:131], v[132:135], v[32:47]
	v_mfma_f32_32x32x16_bf16 v[0:15], v[128:131], v[136:139], v[0:15]
	ds_read_b128 v[128:131], v141
	ds_read_b128 v[132:135], v152
	ds_read_b128 v[154:157], v152 offset:4096
	v_or_b32_e32 v152, s27, v148
	v_cmp_lt_i32_e64 s[38:39], 15, v152
	s_waitcnt lgkmcnt(0)
	v_mfma_f32_32x32x16_bf16 v[96:111], v[128:131], v[132:135], v[96:111]
	v_mfma_f32_32x32x16_bf16 v[64:79], v[128:131], v[154:157], v[64:79]
	ds_read_b128 v[128:131], v141 offset:4096
	s_waitcnt lgkmcnt(0)
	v_mfma_f32_32x32x16_bf16 v[112:127], v[128:131], v[132:135], v[112:127]
	v_mfma_f32_32x32x16_bf16 v[80:95], v[128:131], v[154:157], v[80:95]
	ds_read_b128 v[128:131], v141 offset:8192
	ds_read_b128 v[138:141], v141 offset:12288
	s_barrier
	s_waitcnt lgkmcnt(0)
	v_mfma_f32_32x32x16_bf16 v[48:63], v[128:131], v[132:135], v[48:63]
	v_mfma_f32_32x32x16_bf16 v[16:31], v[128:131], v[154:157], v[16:31]
	v_subrev_u32_e32 v131, 36, v152
	v_mov_b32_e32 v128, v147
	v_cmp_lt_u32_e32 vcc, 15, v131
	s_and_b64 s[0:1], s[38:39], vcc
	v_bfe_u32 v137, v128, 5, 1
	v_and_b32_e32 v142, 31, v128
	v_mfma_f32_32x32x16_bf16 v[32:47], v[138:141], v[132:135], v[32:47]
	v_mfma_f32_32x32x16_bf16 v[0:15], v[138:141], v[154:157], v[0:15]
	s_and_saveexec_b64 s[4:5], s[0:1]
	s_xor_b64 s[4:5], exec, s[4:5]
	s_cbranch_execz .LBB0_393
	v_cmp_ne_u32_e32 vcc, 34, v152
	s_and_saveexec_b64 s[0:1], vcc
	s_xor_b64 s[6:7], exec, s[0:1]
	s_cbranch_execz .LBB0_390
	s_cmp_gt_u32 s27, 23
	s_mov_b64 s[12:13], -1
	s_cbranch_scc0 .LBB0_373
	v_cmp_lt_u32_e32 vcc, 29, v152
	s_and_saveexec_b64 s[12:13], vcc
	s_xor_b64 s[12:13], exec, s[12:13]
	s_cbranch_execz .LBB0_370
	v_cmp_lt_u32_e32 vcc, 33, v152
	s_and_saveexec_b64 s[16:17], vcc
	s_xor_b64 s[16:17], exec, s[16:17]
	s_cbranch_execz .LBB0_367
	s_cmp_gt_u32 s27, 59
	s_mov_b64 s[0:1], -1
	s_cbranch_scc0 .LBB0_363
	s_cmpk_gt_u32 s27, 0x53
	v_lshlrev_b32_e32 v129, 6, v152
	s_mov_b64 s[8:9], -1
	s_mov_b64 s[10:11], -1
	s_cbranch_scc0 .LBB0_361
	s_add_u32 s14, s2, 0x11fd6100
	s_addc_u32 s15, s3, 0
	v_add_u32_e32 v128, 0xffffeb00, v129
	s_mov_b64 s[10:11], 0
